# GQA main loop: defer 8 of 32 v_exp per tile from the producer step's last PV gaps to the consumer step's QK half
# speedup vs baseline: 1.0136x; 1.0136x over previous
;     const int tid = opaque_tid(), lane = tid & 63, r32 = lane & 31, hi = lane >> 5; const int wid = __builtin_amdgcn_readfirstlane(tid >> 6);
;     const bf16_t* Qw = Q + (long)(wid * QBLK) * PITCH;
;     const unsigned lds0 = (unsigned)(uintptr_t)shm;
;     float* wsf = (float*)(shm + LDS_WS) + wid * 64;
;     const unsigned kvo = (unsigned)((lane * PITCH + wid * 8) * 2);
;     const unsigned vvo = (unsigned)(((16 * (wid & 3) + (lane >> 2)) * PITCH + (wid >> 2) * 32 + (lane & 3) * 8) * 2);
;     const unsigned kdst = lds0 + LDS_K + wid * 1024, vdst = lds0 + LDS_V + wid * 1024;
;     ...
;     const char* Kbase = shm + LDS_K; bf16x8 kf[8];
;     const lds_cptr shm3 = (lds_cptr)shm; const lds_cptr kp0 = shm3 + LDS_K + hi * 1024 + r32 * 16; const lds_cptr vp0 = shm3 + LDS_V + ((lane >> 4) & 1) * 32 + (lane & 3) * 8 + (4 * hi + ((lane & 15) >> 2)) * 64;
;     DMA_K(0, 0); DMA_V(0, 0); DMA_K(1, SLOTB);
;     bf16x8 qr[4];
; #pragma unroll
;     for (int d0 = 0; d0 < 4; ++d0) qr[d0] = *reinterpret_cast<const bf16x8*>(&Qw[(long)r32 * PITCH + d0 * 16 + hi * 8]);
;     float mhat = (MODE == 0) ? bref : 0.f, l_reg = 0.f; f32x16 o[2]; o[0] = f32x16{}; o[1] = f32x16{}; f32x16 negm = f32x16{};
;     if (MODE == 0) { _Pragma("unroll") for (int r = 0; r < 16; ++r) negm[r] = -bref; }
;     if (MODE != 1) asm volatile("" : "+v"(negm));
;     int na_gr = 0, na_rs = 0, na_qc = 0, na_cs = 0;
;     if (MODE == 1) { na_gr = r0 + (wid >> 1); na_rs = min(max(na_gr - 4, 0), 120); na_qc = 32 * (wid & 1) + r32; na_cs = min(max(na_qc - 8, 0), 48); }
;     ...
;     bool resc = false;
;     ...
;     f32x16 pA0, pA1, pB0, pB1;
;     int sl_prev = 0, sl_cur = 0, sl_next = SLOTB;
;     ...
;     DMA_K(2, 2 * SLOTB);
;     WAIT_BAR(3);
;     qkt(pA0, pA1, Kbase, qr, negm, r32, hi); asm volatile("s_nop 15\n\ts_nop 7" : "+v"(pA0), "+v"(pA1));
;     START(pA0, pA1);
;     _Pragma("unroll") for (int r = 0; r < 16; ++r) pA1[r] = __builtin_amdgcn_exp2f(pA1[r]);
;     WAIT_BAR(0);
; __global__ void __launch_bounds__(NTHREADS, 2) mega_fwd(Params P) {
;     ...
;                 if (idx < n_gqa) {
;                     const int qb = idx / 12, r12 = idx % 12, b = r12 / 6, h = r12 % 6; const size_t rb = (size_t)b * RPB;
;                     ap::unit<8, 0>(qkv + (rb + 256 * qb) * DIN + C_QC + 64 * h, qkv + rb * DIN + C_KC + 64 * (h / 3), qkv + rb * DIN + C_VC + 64 * (h / 3),
.LBB0_874:
	s_andn2_b64 vcc, exec, s[0:1]
	s_cbranch_vccnz .LBB0_439
	s_mul_hi_i32 s0, s48, 0x2aaaaaab
	s_lshr_b32 s1, s0, 31
	s_ashr_i32 s3, s0, 1
	s_add_i32 s3, s3, s1
	s_mul_i32 s0, s3, 12
	s_sub_i32 s0, s48, s0
	s_mul_i32 s1, s0, 43
	s_bfe_u32 s2, s1, 0x1000f
	s_bfe_u32 s1, s1, 0x80008
	s_add_i32 s1, s1, s2
	s_sext_i32_i8 s18, s1
	s_mul_i32 s1, s1, 6
	s_mul_i32 s9, s18, 0x2100
	s_lshl_b32 s4, s3, 8
	s_sub_i32 s8, s0, s1
	s_ashr_i32 s5, s9, 31
	s_ashr_i32 s6, s4, 31
	s_add_u32 s4, s9, s4
	s_addc_u32 s5, s5, s6
	s_mul_i32 s6, s5, 0x1200
	s_mul_hi_u32 s7, s4, 0x1200
	s_mov_b64 s[0:1], s[76:77]
	s_add_i32 s7, s7, s6
	s_mul_i32 s6, s4, 0x1200
	s_sext_i32_i8 s2, s8
	s_add_u32 s10, s0, s6
	s_addc_u32 s11, s1, s7
	s_lshl_b32 s0, s2, 6
	s_ashr_i32 s1, s0, 31
	s_lshl_b64 s[6:7], s[0:1], 1
	s_add_u32 s26, s10, s6
	s_addc_u32 s27, s11, s7
	s_mov_b64 s[0:1], s[76:77]
	s_mul_i32 s10, s18, 0x2520000
	s_mul_hi_i32 s9, s9, 0x1200
	s_add_u32 s2, s0, s10
	s_addc_u32 s22, s1, s9
	s_bfe_i32 s0, s8, 0x80000
	s_mulk_i32 s0, 0x56
	s_bfe_u32 s1, s0, 0x1000f
	s_bfe_u32 s0, s0, 0x80008
	s_add_i32 s0, s0, s1
	s_sext_i32_i8 s0, s0
	s_lshl_b32 s0, s0, 6
	s_ashr_i32 s1, s0, 31
	s_lshl_b64 s[16:17], s[0:1], 1
	s_add_u32 s30, s2, s16
	s_addc_u32 s34, s22, s17
	s_add_u32 s14, s30, 0xe400300
	s_addc_u32 s15, s34, 0
	s_mov_b64 s[0:1], s[76:77]
	s_add_u32 s23, s0, s10
	s_addc_u32 s24, s1, s9
	s_add_u32 s35, s23, s16
	s_addc_u32 s36, s24, s17
	v_readlane_b32 s20, v252, 9
	s_add_u32 s12, s35, 0xe401100
	s_mov_b64 s[10:11], s[76:77]
	s_mov_b64 s[8:9], s[76:77]
	s_mov_b64 s[0:1], s[76:77]
	v_readlane_b32 s21, v252, 10
	s_addc_u32 s13, s36, 0
	s_lshl_b64 s[20:21], s[20:21], 2
	s_add_u32 s0, s0, s20
	s_addc_u32 s1, s1, s21
	v_mov_b32_e32 v0, s0
	s_mov_b32 s0, 0x184000
	v_mov_b32_e32 v3, s1
	v_add_co_u32_e32 v2, vcc, s0, v0
	v_mov_b32_e32 v194, 0
	s_nop 0
	v_addc_co_u32_e32 v3, vcc, 0, v3, vcc
	flat_load_dword v6, v[2:3]
	v_mov_b32 v14, v214
	s_waitcnt vmcnt(0) lgkmcnt(0)
	v_xor_b32_e32 v50, 0x80000000, v6
	v_readfirstlane_b32 s25, v14
	s_ashr_i32 s19, s25, 6
	s_lshl_b32 s0, s19, 5
	s_ashr_i32 s1, s0, 31
	s_mul_i32 s20, s19, 0x24000
	s_mul_hi_i32 s21, s0, 0x1200
	s_add_u32 s28, s26, s20
	s_addc_u32 s29, s27, s21
	s_lshl_b32 s20, s19, 4
	v_and_b32_e32 v15, 63, v14
	v_mov_b32_e32 v0, s20
	v_mad_u32_u24 v193, v15, s80, v0
	v_bfe_u32 v0, v14, 2, 4
	v_and_or_b32 v0, s20, 48, v0
	s_ashr_i32 s20, s25, 3
	s_and_b32 s20, s20, 0x7fffffe0
	v_mov_b32_e32 v2, s20
	v_mad_u32_u24 v0, v0, s81, v2
	v_lshlrev_b32_e32 v2, 3, v14
	v_and_b32_e32 v187, 24, v2
	v_and_b32_e32 v17, 31, v14
	v_or_b32_e32 v0, v0, v187
	s_lshl_b32 s21, s19, 10
	v_lshlrev_b32_e32 v192, 1, v0
	s_cmp_lg_u32 0, -1
	v_mul_u32_u24_e32 v0, 0x900, v17
	v_bfe_u32 v186, v14, 5, 1
	s_cselect_b32 s20, 0, 0
	v_lshlrev_b32_e32 v0, 1, v0
	s_add_i32 s26, s21, s20
	v_lshl_or_b32 v0, v186, 4, v0
	s_add_i32 s20, s26, 0x6000
	s_mov_b32 s27, m0
	s_mov_b32 m0, s26
	s_nop 0
	global_load_lds_dwordx4 v193, s[14:15]
	s_mov_b32 m0, s27
	v_lshl_add_u64 v[2:3], s[28:29], 0, v[0:1]
	s_mov_b32 s27, m0
	s_mov_b32 m0, s20
	s_nop 0
	global_load_lds_dwordx4 v192, s[12:13]
	s_mov_b32 m0, s27
	s_add_u32 s38, s30, 0xe448300
	v_add_co_u32_e32 v4, vcc, s82, v2
	s_addc_u32 s39, s34, 0
	s_add_i32 s27, s26, 0x2000
	s_mov_b32 s31, m0
	s_mov_b32 m0, s27
	s_nop 0
	global_load_lds_dwordx4 v193, s[38:39]
	s_mov_b32 m0, s31
	v_addc_co_u32_e32 v5, vcc, 0, v3, vcc
	flat_load_dwordx4 v[162:165], v[4:5]
	s_mov_b64 s[28:29], 0xe400000
	v_lshl_add_u64 v[2:3], v[2:3], 0, s[28:29]
	flat_load_dwordx4 v[158:161], v[2:3] offset:32
	flat_load_dwordx4 v[154:157], v[2:3] offset:64
	flat_load_dwordx4 v[150:153], v[2:3] offset:96
	v_mov_b32_e32 v51, v50
	v_mov_b32_e32 v52, v50
	v_mov_b32_e32 v53, v50
	v_mov_b32_e32 v54, v50
	v_mov_b32_e32 v55, v50
	v_mov_b32_e32 v56, v50
	v_mov_b32_e32 v57, v50
	v_mov_b32_e32 v58, v50
	v_mov_b32_e32 v59, v50
	v_mov_b32_e32 v60, v50
	v_mov_b32_e32 v61, v50
	v_mov_b32_e32 v62, v50
	v_mov_b32_e32 v63, v50
	v_mov_b32_e32 v64, v50
	v_mov_b32_e32 v65, v50
	s_add_u32 s28, s30, 0xe490300
	v_lshlrev_b32_e32 v0, 10, v186
	v_lshlrev_b32_e32 v4, 4, v17
	s_addc_u32 s29, s34, 0
	s_add_i32 s27, s26, 0x4000
	s_mov_b32 s31, m0
	s_mov_b32 m0, s27
	s_nop 0
	global_load_lds_dwordx4 v193, s[28:29]
	s_mov_b32 m0, s31
	v_add3_u32 v191, 0, v0, v4
	s_waitcnt vmcnt(3) lgkmcnt(0)
	s_barrier
	ds_read_b128 v[2:5], v191
	ds_read_b128 v[6:9], v191 offset:512
	s_waitcnt vmcnt(0) lgkmcnt(0)
	v_mfma_f32_32x32x16_bf16 v[34:49], v[2:5], v[162:165], v[50:65]
	s_add_u32 s38, s30, 0xe4d8300
	s_addc_u32 s39, s34, 0
	s_add_u32 s34, s35, 0xe449100
	s_addc_u32 s35, s36, 0
	v_lshlrev_b32_e32 v0, 1, v14
	v_and_b32_e32 v188, 32, v0
	v_lshlrev_b32_e32 v0, 8, v186
	v_mfma_f32_32x32x16_bf16 v[18:33], v[6:9], v[162:165], v[50:65]
	ds_read_b128 v[2:5], v191 offset:2048
	ds_read_b128 v[6:9], v191 offset:2560
	s_mov_b32 s31, 0
	s_mov_b32 s27, -1
	s_movk_i32 s29, 0x2000
	s_movk_i32 s28, 0x4000
	s_waitcnt lgkmcnt(1)
	v_mfma_f32_32x32x16_bf16 v[34:49], v[2:5], v[158:161], v[34:49]
	s_waitcnt lgkmcnt(0)
	v_mfma_f32_32x32x16_bf16 v[18:33], v[6:9], v[158:161], v[18:33]
	ds_read_b128 v[2:5], v191 offset:4096
	ds_read_b128 v[6:9], v191 offset:4608
	s_waitcnt lgkmcnt(1)
	v_mfma_f32_32x32x16_bf16 v[34:49], v[2:5], v[154:157], v[34:49]
	s_waitcnt lgkmcnt(0)
	v_mfma_f32_32x32x16_bf16 v[18:33], v[6:9], v[154:157], v[18:33]
	ds_read_b128 v[2:5], v191 offset:6144
	ds_read_b128 v[6:9], v191 offset:6656
	s_waitcnt lgkmcnt(1)
	v_mfma_f32_32x32x16_bf16 v[34:49], v[2:5], v[150:153], v[34:49]
	v_lshlrev_b32_e32 v3, 4, v14
	v_add_u32_e32 v2, 0, v188
	v_and_or_b32 v189, v3, s83, v0
	v_add3_u32 v190, v2, v187, v189
	s_waitcnt lgkmcnt(0)
	v_mfma_f32_32x32x16_bf16 v[18:33], v[6:9], v[150:153], v[18:33]
	s_nop 15
	s_nop 7
	s_waitcnt vmcnt(0) lgkmcnt(0)
	s_barrier
; #define WAIT_BAR(N) asm volatile("s_waitcnt vmcnt(" #N ") lgkmcnt(0)\n\ts_barrier" ::: "memory")
; #define DMA_K(t, slot) glds16s(kvo, Kh + (long)TROW(t) * PITCH, (unsigned)__builtin_amdgcn_readfirstlane(kdst + (slot)))
; #define DMA_V(t, slot) glds16s(vvo, Vh + (long)TROW(t) * PITCH, (unsigned)__builtin_amdgcn_readfirstlane(vdst + (slot)))
; #define RESC() do { if (resc) { asm volatile("s_waitcnt lgkmcnt(0)" ::: "memory"); \
;       _Pragma("unroll") for (int d_ = 0; d_ < 2; ++d_) _Pragma("unroll") for (int r = 0; r < 16; ++r) o[d_][r] *= wsf[crow(r, hi)]; } } while (0)
; #define ROT() do { sl_prev = sl_cur; sl_cur = sl_next; sl_next = (sl_next == (NSLOT - 1) * SLOTB) ? 0 : sl_next + SLOTB; } while (0)
;     ...
;     DMA_K(2, 2 * SLOTB);
;     WAIT_BAR(3);
;     qkt(pA0, pA1, Kbase, qr, negm, r32, hi); asm volatile("s_nop 15\n\ts_nop 7" : "+v"(pA0), "+v"(pA1));
;     START(pA0, pA1);
;     _Pragma("unroll") for (int r = 0; r < 16; ++r) pA1[r] = __builtin_amdgcn_exp2f(pA1[r]);
;     WAIT_BAR(0);
;     DMA_K(3, 0); DMA_V(1, SLOTB);
;     ROT();
;     kload8(kf, kp0 + sl_cur);
;     WAIT_BAR(2);
;     s16x4 vlo[8], vhi[8]; u32x4 pw0, pw1, pw2, pw3;
;     ...
;     int t = 1;
;     for (; t + 5 < NT; t += 2) {
;         STEP(pB0, pB1, pA0, pA1, t, true, true, true);     WAIT_BAR(2); RESC(); ROT();
;         STEP(pA0, pA1, pB0, pB1, t + 1, true, true, true); WAIT_BAR(2); RESC(); ROT();
	s_mov_b32 s30, m0
	s_mov_b32 m0, s26
	s_nop 0
	global_load_lds_dwordx4 v193, s[38:39]
	s_mov_b32 m0, s30
	s_add_i32 s30, s26, 0x8000
	s_mov_b32 s36, m0
	s_mov_b32 m0, s30
	s_nop 0
	global_load_lds_dwordx4 v192, s[34:35]
	s_mov_b32 m0, s36
	ds_read_b128 v[98:101], v191 offset:8192
	ds_read_b128 v[170:173], v191 offset:8704
	ds_read_b128 v[174:177], v191 offset:10240
	ds_read_b128 v[166:169], v191 offset:10752
	ds_read_b128 v[142:145], v191 offset:12288
	ds_read_b128 v[138:141], v191 offset:12800
	ds_read_b128 v[134:137], v191 offset:14336
	ds_read_b128 v[130:133], v191 offset:14848
	v_exp_f32_e32 v82, v34
	v_exp_f32_e32 v83, v35
	v_exp_f32_e32 v84, v36
	v_exp_f32_e32 v85, v37
	v_exp_f32_e32 v86, v38
	v_exp_f32_e32 v87, v39
	v_exp_f32_e32 v88, v40
	v_exp_f32_e32 v89, v41
	v_exp_f32_e32 v90, v42
	v_exp_f32_e32 v91, v43
	v_exp_f32_e32 v92, v44
	v_exp_f32_e32 v93, v45
	v_exp_f32_e32 v94, v46
	v_exp_f32_e32 v95, v47
	v_exp_f32_e32 v96, v48
	v_exp_f32_e32 v97, v49
	v_exp_f32_e32 v66, v18
	v_exp_f32_e32 v67, v19
	v_exp_f32_e32 v68, v20
	v_exp_f32_e32 v69, v21
	v_exp_f32_e32 v70, v22
	v_exp_f32_e32 v71, v23
	v_exp_f32_e32 v72, v24
	v_exp_f32_e32 v73, v25
	v_mov_b32_e32 v74, v26
	v_mov_b32_e32 v75, v27
	v_mov_b32_e32 v76, v28
	v_mov_b32_e32 v77, v29
	v_mov_b32_e32 v78, v30
	v_mov_b32_e32 v79, v31
	v_mov_b32_e32 v80, v32
	v_mov_b32_e32 v81, v33
	s_waitcnt vmcnt(2) lgkmcnt(0)
	s_barrier
	v_mov_b32_e32 v18, 0
	v_mov_b32_e32 v19, v194
	v_mov_b32_e32 v20, v194
	v_mov_b32_e32 v21, v194
	v_mov_b32_e32 v22, v194
	v_mov_b32_e32 v23, v194
	v_mov_b32_e32 v24, v194
	v_mov_b32_e32 v25, v194
	v_mov_b32_e32 v26, v194
	v_mov_b32_e32 v27, v194
	v_mov_b32_e32 v28, v194
	v_mov_b32_e32 v29, v194
	v_mov_b32_e32 v30, v194
	v_mov_b32_e32 v31, v194
	v_mov_b32_e32 v32, v194
	v_mov_b32_e32 v33, v194
	v_mov_b32_e32 v34, 0
	v_mov_b32_e32 v35, v194
	v_mov_b32_e32 v36, v194
	v_mov_b32_e32 v37, v194
	v_mov_b32_e32 v38, v194
	v_mov_b32_e32 v39, v194
	v_mov_b32_e32 v40, v194
	v_mov_b32_e32 v41, v194
	v_mov_b32_e32 v42, v194
	v_mov_b32_e32 v43, v194
	v_mov_b32_e32 v44, v194
	v_mov_b32_e32 v45, v194
	v_mov_b32_e32 v46, v194
	v_mov_b32_e32 v47, v194
	v_mov_b32_e32 v48, v194
	v_mov_b32_e32 v49, v194
.LBB0_876:
	v_add_u32_e32 v195, s31, v190
	ds_read_b64_tr_b16 v[182:183], v195 offset:24576
	ds_read_b64_tr_b16 v[184:185], v195 offset:25088
	v_add_f32_e32 v2, v82, v83
	v_add_f32_e32 v2, v84, v2
	v_add_f32_e32 v2, v85, v2
	v_add_f32_e32 v2, v86, v2
	v_add_f32_e32 v2, v87, v2
	v_cvt_pk_bf16_f32 v146, v82, v83
	v_cvt_pk_bf16_f32 v147, v84, v85
	s_waitcnt lgkmcnt(9)
	v_mfma_f32_32x32x16_bf16 v[114:129], v[98:101], v[162:165], v[50:65]
	ds_read_b64_tr_b16 v[178:179], v195 offset:28672
	ds_read_b64_tr_b16 v[180:181], v195 offset:29184
	s_waitcnt lgkmcnt(10)
	v_mfma_f32_32x32x16_bf16 v[98:113], v[170:173], v[162:165], v[50:65]
	v_add_f32_e32 v2, v88, v2
	v_add_f32_e32 v2, v89, v2
	v_add_f32_e32 v2, v90, v2
	v_add_f32_e32 v2, v91, v2
	v_cvt_pk_bf16_f32 v148, v86, v87
	v_cvt_pk_bf16_f32 v149, v88, v89
	ds_read_b64_tr_b16 v[82:83], v195 offset:25600
	ds_read_b64_tr_b16 v[84:85], v195 offset:26112
	v_add_f32_e32 v2, v92, v2
	v_add_f32_e32 v2, v93, v2
	v_add_f32_e32 v2, v94, v2
	v_add_f32_e32 v2, v95, v2
	v_cvt_pk_bf16_f32 v10, v90, v91
	v_cvt_pk_bf16_f32 v11, v92, v93
	s_waitcnt lgkmcnt(11)
	v_mfma_f32_32x32x16_bf16 v[114:129], v[174:177], v[158:161], v[114:129]
	v_exp_f32_e32 v74, v74
	v_exp_f32_e32 v75, v75
	ds_read_b64_tr_b16 v[86:87], v195 offset:29696
	ds_read_b64_tr_b16 v[88:89], v195 offset:30208
	s_waitcnt lgkmcnt(12)
	v_mfma_f32_32x32x16_bf16 v[98:113], v[166:169], v[158:161], v[98:113]
	v_exp_f32_e32 v76, v76
	v_exp_f32_e32 v77, v77
	v_exp_f32_e32 v78, v78
	v_add_f32_e32 v2, v96, v2
	v_add_f32_e32 v2, v97, v2
	v_add_f32_e32 v2, v66, v2
	v_add_f32_e32 v2, v67, v2
	v_cvt_pk_bf16_f32 v12, v94, v95
	v_cvt_pk_bf16_f32 v13, v96, v97
	ds_read_b64_tr_b16 v[90:91], v195 offset:26624
	ds_read_b64_tr_b16 v[92:93], v195 offset:27136
	v_add_f32_e32 v2, v68, v2
	v_add_f32_e32 v2, v69, v2
	v_add_f32_e32 v2, v70, v2
	v_add_f32_e32 v2, v71, v2
	v_cvt_pk_bf16_f32 v6, v66, v67
	v_cvt_pk_bf16_f32 v7, v68, v69
	s_waitcnt lgkmcnt(13)
	v_mfma_f32_32x32x16_bf16 v[114:129], v[142:145], v[154:157], v[114:129]
	v_exp_f32_e32 v79, v79
	v_exp_f32_e32 v80, v80
	v_exp_f32_e32 v81, v81
	ds_read_b64_tr_b16 v[66:67], v195 offset:30720
	ds_read_b64_tr_b16 v[68:69], v195 offset:31232
	s_waitcnt lgkmcnt(14)
	v_mfma_f32_32x32x16_bf16 v[98:113], v[138:141], v[154:157], v[98:113]
	v_add_f32_e32 v2, v72, v2
	v_add_f32_e32 v2, v73, v2
	v_add_f32_e32 v2, v74, v2
	v_add_f32_e32 v2, v75, v2
	v_cvt_pk_bf16_f32 v8, v70, v71
	v_cvt_pk_bf16_f32 v9, v72, v73
	ds_read_b64_tr_b16 v[70:71], v195 offset:27648
	ds_read_b64_tr_b16 v[72:73], v195 offset:28160
	v_add_f32_e32 v2, v76, v2
	v_add_f32_e32 v2, v77, v2
	v_add_f32_e32 v2, v78, v2
	v_add_f32_e32 v94, v79, v2
	v_cvt_pk_bf16_f32 v2, v74, v75
	v_cvt_pk_bf16_f32 v3, v76, v77
	s_waitcnt lgkmcnt(14)
	v_mfma_f32_32x32x16_bf16 v[114:129], v[134:137], v[150:153], v[114:129]
	ds_read_b64_tr_b16 v[74:75], v195 offset:31744
	ds_read_b64_tr_b16 v[76:77], v195 offset:32256
	v_mfma_f32_32x32x16_bf16 v[98:113], v[130:133], v[150:153], v[98:113]
	v_add_f32_e32 v4, v80, v94
	v_add_f32_e32 v4, v81, v4
	v_add_f32_e32 v195, 0, v4
	v_cvt_pk_bf16_f32 v4, v78, v79
	v_cvt_pk_bf16_f32 v5, v80, v81
	s_add_u32 s31, s2, s16
	s_addc_u32 s34, s22, s17
	s_add_u32 s36, s31, 0xe520300
	s_addc_u32 s37, s34, 0
	s_add_i32 s30, s29, s26
	s_mov_b32 s35, m0
	s_mov_b32 m0, s30
	s_nop 0
	global_load_lds_dwordx4 v193, s[36:37]
	s_mov_b32 m0, s35
	s_add_u32 s35, s23, s16
	s_addc_u32 s36, s24, s17
	s_add_u32 s38, s35, 0xe491100
	s_addc_u32 s39, s36, 0
	s_add_i32 s30, s28, s20
	s_mov_b32 s37, m0
	s_mov_b32 m0, s30
	s_nop 0
	global_load_lds_dwordx4 v192, s[38:39]
	s_mov_b32 m0, s37
	s_waitcnt lgkmcnt(14)
; #define WAIT_BAR(N) asm volatile("s_waitcnt vmcnt(" #N ") lgkmcnt(0)\n\ts_barrier" ::: "memory")
; #define RESC() do { if (resc) { asm volatile("s_waitcnt lgkmcnt(0)" ::: "memory"); \
;       _Pragma("unroll") for (int d_ = 0; d_ < 2; ++d_) _Pragma("unroll") for (int r = 0; r < 16; ++r) o[d_][r] *= wsf[crow(r, hi)]; } } while (0)
; #define ROT() do { sl_prev = sl_cur; sl_cur = sl_next; sl_next = (sl_next == (NSLOT - 1) * SLOTB) ? 0 : sl_next + SLOTB; } while (0)
;     ...
;     int t = 1;
;     for (; t + 5 < NT; t += 2) {
;         STEP(pB0, pB1, pA0, pA1, t, true, true, true);     WAIT_BAR(2); RESC(); ROT();
;         STEP(pA0, pA1, pB0, pB1, t + 1, true, true, true); WAIT_BAR(2); RESC(); ROT();
	v_mfma_f32_32x32x16_bf16 v[18:33], v[146:149], v[182:185], v[18:33]
	v_exp_f32_e32 v114, v114
	v_exp_f32_e32 v115, v115
	v_exp_f32_e32 v116, v116
	v_exp_f32_e32 v117, v117
	s_waitcnt lgkmcnt(12)
	v_mfma_f32_32x32x16_bf16 v[34:49], v[146:149], v[178:181], v[34:49]
	v_exp_f32_e32 v118, v118
	v_exp_f32_e32 v119, v119
	v_exp_f32_e32 v120, v120
	v_exp_f32_e32 v121, v121
	v_add_u32_e32 v94, s28, v191
	ds_read_b128 v[78:81], v94
	ds_read_b128 v[134:137], v94 offset:512
	s_waitcnt lgkmcnt(12)
	v_mfma_f32_32x32x16_bf16 v[18:33], v[10:13], v[82:85], v[18:33]
	v_exp_f32_e32 v122, v122
	v_exp_f32_e32 v123, v123
	v_exp_f32_e32 v124, v124
	v_exp_f32_e32 v125, v125
	ds_read_b128 v[138:141], v94 offset:2048
	ds_read_b128 v[142:145], v94 offset:2560
	s_waitcnt lgkmcnt(12)
	v_mfma_f32_32x32x16_bf16 v[34:49], v[10:13], v[86:89], v[34:49]
	v_exp_f32_e32 v126, v126
	v_exp_f32_e32 v127, v127
	v_exp_f32_e32 v128, v128
	v_exp_f32_e32 v129, v129
	ds_read_b128 v[166:169], v94 offset:4096
	ds_read_b128 v[170:173], v94 offset:4608
	s_waitcnt lgkmcnt(12)
	v_mfma_f32_32x32x16_bf16 v[18:33], v[6:9], v[90:93], v[18:33]
	v_exp_f32_e32 v98, v98
	v_exp_f32_e32 v99, v99
	v_exp_f32_e32 v100, v100
	v_exp_f32_e32 v101, v101
	ds_read_b128 v[174:177], v94 offset:6144
	ds_read_b128 v[130:133], v94 offset:6656
	s_waitcnt lgkmcnt(12)
	v_mfma_f32_32x32x16_bf16 v[34:49], v[6:9], v[66:69], v[34:49]
	v_exp_f32_e32 v102, v102
	v_exp_f32_e32 v103, v103
	v_exp_f32_e32 v104, v104
	v_exp_f32_e32 v105, v105
	s_waitcnt lgkmcnt(10)
	v_mfma_f32_32x32x16_bf16 v[18:33], v[2:5], v[70:73], v[18:33]
	s_waitcnt lgkmcnt(8)
	v_mfma_f32_32x32x16_bf16 v[34:49], v[2:5], v[74:77], v[34:49]
	s_waitcnt vmcnt(2) lgkmcnt(0)
	s_barrier
	s_add_i32 s30, s28, 0x2000
	s_cmpk_lg_i32 s28, 0x4000
	s_cselect_b32 s30, s30, 0
	v_add_u32_e32 v196, s29, v190
	ds_read_b64_tr_b16 v[178:179], v196 offset:24576
	ds_read_b64_tr_b16 v[180:181], v196 offset:25088
	s_waitcnt lgkmcnt(9)
	v_mfma_f32_32x32x16_bf16 v[82:97], v[78:81], v[162:165], v[50:65]
	v_add_f32_e32 v2, v114, v115
	v_add_f32_e32 v2, v116, v2
	v_add_f32_e32 v2, v117, v2
	v_add_f32_e32 v2, v118, v2
	v_add_f32_e32 v2, v119, v2
	v_cvt_pk_bf16_f32 v146, v114, v115
	v_cvt_pk_bf16_f32 v147, v116, v117
	ds_read_b64_tr_b16 v[182:183], v196 offset:28672
	ds_read_b64_tr_b16 v[184:185], v196 offset:29184
	s_waitcnt lgkmcnt(10)
	v_mfma_f32_32x32x16_bf16 v[66:81], v[134:137], v[162:165], v[50:65]
	v_add_f32_e32 v2, v120, v2
	v_add_f32_e32 v2, v121, v2
	v_add_f32_e32 v2, v122, v2
	v_add_f32_e32 v2, v123, v2
	v_cvt_pk_bf16_f32 v148, v118, v119
	v_cvt_pk_bf16_f32 v149, v120, v121
	ds_read_b64_tr_b16 v[114:115], v196 offset:25600
	ds_read_b64_tr_b16 v[116:117], v196 offset:26112
	s_waitcnt lgkmcnt(11)
	v_mfma_f32_32x32x16_bf16 v[82:97], v[138:141], v[158:161], v[82:97]
	v_exp_f32_e32 v106, v106
	v_exp_f32_e32 v107, v107
	v_add_f32_e32 v2, v124, v2
	v_add_f32_e32 v2, v125, v2
	v_add_f32_e32 v2, v126, v2
	v_add_f32_e32 v2, v127, v2
	v_cvt_pk_bf16_f32 v10, v122, v123
	v_cvt_pk_bf16_f32 v11, v124, v125
	ds_read_b64_tr_b16 v[118:119], v196 offset:29696
	ds_read_b64_tr_b16 v[120:121], v196 offset:30208
	s_waitcnt lgkmcnt(12)
	v_mfma_f32_32x32x16_bf16 v[66:81], v[142:145], v[158:161], v[66:81]
	v_exp_f32_e32 v108, v108
	v_exp_f32_e32 v109, v109
	v_exp_f32_e32 v110, v110
	v_add_f32_e32 v2, v128, v2
	v_add_f32_e32 v2, v129, v2
	v_add_f32_e32 v2, v98, v2
	v_add_f32_e32 v2, v99, v2
	v_cvt_pk_bf16_f32 v12, v126, v127
	v_cvt_pk_bf16_f32 v13, v128, v129
	ds_read_b64_tr_b16 v[122:123], v196 offset:26624
	ds_read_b64_tr_b16 v[124:125], v196 offset:27136
	s_waitcnt lgkmcnt(13)
	v_mfma_f32_32x32x16_bf16 v[82:97], v[166:169], v[154:157], v[82:97]
	v_exp_f32_e32 v111, v111
	v_exp_f32_e32 v112, v112
	v_exp_f32_e32 v113, v113
	v_add_f32_e32 v2, v100, v2
	v_add_f32_e32 v2, v101, v2
	v_add_f32_e32 v2, v102, v2
	v_add_f32_e32 v2, v103, v2
	v_cvt_pk_bf16_f32 v6, v98, v99
	v_cvt_pk_bf16_f32 v7, v100, v101
	ds_read_b64_tr_b16 v[126:127], v196 offset:30720
	ds_read_b64_tr_b16 v[128:129], v196 offset:31232
	s_waitcnt lgkmcnt(14)
	v_mfma_f32_32x32x16_bf16 v[66:81], v[170:173], v[154:157], v[66:81]
	v_add_f32_e32 v2, v104, v2
	v_add_f32_e32 v2, v105, v2
	v_add_f32_e32 v2, v106, v2
	v_add_f32_e32 v2, v107, v2
	v_cvt_pk_bf16_f32 v8, v102, v103
	v_cvt_pk_bf16_f32 v9, v104, v105
	ds_read_b64_tr_b16 v[102:103], v196 offset:27648
	ds_read_b64_tr_b16 v[104:105], v196 offset:28160
	s_waitcnt lgkmcnt(14)
	v_mfma_f32_32x32x16_bf16 v[82:97], v[174:177], v[150:153], v[82:97]
	v_add_f32_e32 v2, v108, v2
	v_add_f32_e32 v2, v109, v2
	v_add_f32_e32 v2, v110, v2
	v_add_f32_e32 v98, v111, v2
	v_cvt_pk_bf16_f32 v2, v106, v107
	v_cvt_pk_bf16_f32 v3, v108, v109
	ds_read_b64_tr_b16 v[106:107], v196 offset:31744
	ds_read_b64_tr_b16 v[108:109], v196 offset:32256
	v_mfma_f32_32x32x16_bf16 v[66:81], v[130:133], v[150:153], v[66:81]
	v_add_f32_e32 v4, v112, v98
	v_add_f32_e32 v4, v113, v4
	v_add_f32_e32 v196, 0, v4
	v_cvt_pk_bf16_f32 v4, v110, v111
	v_cvt_pk_bf16_f32 v5, v112, v113
	s_add_u32 s38, s31, 0xe568300
	s_addc_u32 s39, s34, 0
	s_add_i32 s29, s28, s26
	s_mov_b32 s31, m0
	s_mov_b32 m0, s29
	s_nop 0
	global_load_lds_dwordx4 v193, s[38:39]
	s_mov_b32 m0, s31
	s_add_u32 s34, s35, 0xe4d9100
	s_addc_u32 s35, s36, 0
	s_add_i32 s29, s30, s20
	s_mov_b32 s31, m0
	s_mov_b32 m0, s29
	s_nop 0
	global_load_lds_dwordx4 v192, s[34:35]
	s_mov_b32 m0, s31
	s_waitcnt lgkmcnt(14)
	v_mfma_f32_32x32x16_bf16 v[18:33], v[146:149], v[178:181], v[18:33]
	v_exp_f32_e32 v82, v82
	v_exp_f32_e32 v83, v83
	v_exp_f32_e32 v84, v84
	v_exp_f32_e32 v85, v85
	s_waitcnt lgkmcnt(12)
; #define WAIT_BAR(N) asm volatile("s_waitcnt vmcnt(" #N ") lgkmcnt(0)\n\ts_barrier" ::: "memory")
; #define RESC() do { if (resc) { asm volatile("s_waitcnt lgkmcnt(0)" ::: "memory"); \
;       _Pragma("unroll") for (int d_ = 0; d_ < 2; ++d_) _Pragma("unroll") for (int r = 0; r < 16; ++r) o[d_][r] *= wsf[crow(r, hi)]; } } while (0)
; #define ROT() do { sl_prev = sl_cur; sl_cur = sl_next; sl_next = (sl_next == (NSLOT - 1) * SLOTB) ? 0 : sl_next + SLOTB; } while (0)
; #define ENDW(tt) do { if ((tt) + 3 < NT) { WAIT_BAR(2); } else if ((tt) + 2 < NT) { WAIT_BAR(1); } else { WAIT_BAR(0); } } while (0)
;     ...
;     int t = 1;
;     for (; t + 5 < NT; t += 2) {
;         STEP(pB0, pB1, pA0, pA1, t, true, true, true);     WAIT_BAR(2); RESC(); ROT();
;         STEP(pA0, pA1, pB0, pB1, t + 1, true, true, true); WAIT_BAR(2); RESC(); ROT();
;     }
;     ...
;     for (; t + 1 < NT; t += 2) {
;         STEP(pB0, pB1, pA0, pA1, t, (t + 3 < NT), (t + 1 < NT), (t + 1 < NT));         ENDW(t);     RESC(); ROT();
;         STEP(pA0, pA1, pB0, pB1, t + 1, (t + 4 < NT), (t + 2 < NT), (t + 2 < NT));     ENDW(t + 1); RESC(); ROT();
	v_mfma_f32_32x32x16_bf16 v[34:49], v[146:149], v[182:185], v[34:49]
	v_exp_f32_e32 v86, v86
	v_exp_f32_e32 v87, v87
	v_exp_f32_e32 v88, v88
	v_exp_f32_e32 v89, v89
	v_add_u32_e32 v110, s30, v191
	ds_read_b128 v[98:101], v110
	ds_read_b128 v[170:173], v110 offset:512
	s_waitcnt lgkmcnt(12)
	v_mfma_f32_32x32x16_bf16 v[18:33], v[10:13], v[114:117], v[18:33]
	v_exp_f32_e32 v90, v90
	v_exp_f32_e32 v91, v91
	v_exp_f32_e32 v92, v92
	v_exp_f32_e32 v93, v93
	ds_read_b128 v[174:177], v110 offset:2048
	ds_read_b128 v[166:169], v110 offset:2560
	s_waitcnt lgkmcnt(12)
	v_mfma_f32_32x32x16_bf16 v[34:49], v[10:13], v[118:121], v[34:49]
	v_exp_f32_e32 v94, v94
	v_exp_f32_e32 v95, v95
	v_exp_f32_e32 v96, v96
	v_exp_f32_e32 v97, v97
	ds_read_b128 v[142:145], v110 offset:4096
	ds_read_b128 v[138:141], v110 offset:4608
	s_waitcnt lgkmcnt(12)
	v_mfma_f32_32x32x16_bf16 v[18:33], v[6:9], v[122:125], v[18:33]
	v_exp_f32_e32 v66, v66
	v_exp_f32_e32 v67, v67
	v_exp_f32_e32 v68, v68
	v_exp_f32_e32 v69, v69
	ds_read_b128 v[134:137], v110 offset:6144
	ds_read_b128 v[130:133], v110 offset:6656
	s_waitcnt lgkmcnt(12)
	v_mfma_f32_32x32x16_bf16 v[34:49], v[6:9], v[126:129], v[34:49]
	v_exp_f32_e32 v70, v70
	v_exp_f32_e32 v71, v71
	v_exp_f32_e32 v72, v72
	v_exp_f32_e32 v73, v73
	s_waitcnt lgkmcnt(10)
	v_mfma_f32_32x32x16_bf16 v[18:33], v[2:5], v[102:105], v[18:33]
	s_waitcnt lgkmcnt(8)
	v_mfma_f32_32x32x16_bf16 v[34:49], v[2:5], v[106:109], v[34:49]
	s_add_i32 s34, s30, 0x2000
	s_cmpk_lg_i32 s30, 0x4000
	s_mov_b32 s31, s28
	s_cselect_b32 s28, s34, 0
	s_add_i32 s27, s27, 2
	s_add_u32 s23, s23, 0x90000
	s_addc_u32 s24, s24, 0
	s_waitcnt vmcnt(2) lgkmcnt(0)
	s_barrier
	s_add_u32 s2, s2, 0x90000
	v_add_f32_e32 v2, v194, v195
	s_addc_u32 s22, s22, 0
	s_mov_b32 s29, s30
	v_add_f32_e32 v194, v2, v196
	s_cmpk_gt_u32 s27, 0x7c
	s_cbranch_scc0 .LBB0_876
	v_exp_f32_e32 v74, v74
	v_exp_f32_e32 v75, v75
	v_exp_f32_e32 v76, v76
	v_exp_f32_e32 v77, v77
	v_exp_f32_e32 v78, v78
	v_exp_f32_e32 v79, v79
	v_exp_f32_e32 v80, v80
	v_exp_f32_e32 v81, v81
	s_and_b32 s2, s25, 0x3fffffc0
	s_lshl_b32 s2, s2, 2
	s_add_i32 s2, s2, 0
	ds_read_b64_tr_b16 v[182:183], v190 offset:24576
	ds_read_b64_tr_b16 v[184:185], v190 offset:25088
	v_add_f32_e32 v2, v82, v83
	v_add_f32_e32 v2, v84, v2
	v_add_f32_e32 v2, v85, v2
	v_add_f32_e32 v2, v86, v2
	v_add_f32_e32 v2, v87, v2
	v_cvt_pk_bf16_f32 v146, v82, v83
	v_cvt_pk_bf16_f32 v147, v84, v85
	s_waitcnt lgkmcnt(9)
	v_mfma_f32_32x32x16_bf16 v[114:129], v[98:101], v[162:165], v[50:65]
	ds_read_b64_tr_b16 v[178:179], v190 offset:28672
	ds_read_b64_tr_b16 v[180:181], v190 offset:29184
	v_add_f32_e32 v2, v88, v2
	v_add_f32_e32 v2, v89, v2
	v_add_f32_e32 v2, v90, v2
	v_add_f32_e32 v2, v91, v2
	v_cvt_pk_bf16_f32 v148, v86, v87
	v_cvt_pk_bf16_f32 v149, v88, v89
	s_waitcnt lgkmcnt(10)
	v_mfma_f32_32x32x16_bf16 v[98:113], v[170:173], v[162:165], v[50:65]
	ds_read_b64_tr_b16 v[82:83], v190 offset:25600
	ds_read_b64_tr_b16 v[84:85], v190 offset:26112
	v_add_f32_e32 v2, v92, v2
	v_add_f32_e32 v2, v93, v2
	v_add_f32_e32 v2, v94, v2
	v_add_f32_e32 v2, v95, v2
	v_cvt_pk_bf16_f32 v10, v90, v91
	v_cvt_pk_bf16_f32 v11, v92, v93
	s_waitcnt lgkmcnt(11)
	v_mfma_f32_32x32x16_bf16 v[114:129], v[174:177], v[158:161], v[114:129]
	ds_read_b64_tr_b16 v[86:87], v190 offset:29696
	ds_read_b64_tr_b16 v[88:89], v190 offset:30208
	v_add_f32_e32 v2, v96, v2
	v_add_f32_e32 v2, v97, v2
	v_add_f32_e32 v2, v66, v2
	v_add_f32_e32 v2, v67, v2
	v_cvt_pk_bf16_f32 v12, v94, v95
	v_cvt_pk_bf16_f32 v13, v96, v97
	s_waitcnt lgkmcnt(12)
	v_mfma_f32_32x32x16_bf16 v[98:113], v[166:169], v[158:161], v[98:113]
	ds_read_b64_tr_b16 v[90:91], v190 offset:26624
	ds_read_b64_tr_b16 v[92:93], v190 offset:27136
	v_add_f32_e32 v2, v68, v2
	v_add_f32_e32 v2, v69, v2
	v_add_f32_e32 v2, v70, v2
	v_add_f32_e32 v2, v71, v2
	v_cvt_pk_bf16_f32 v6, v66, v67
	v_cvt_pk_bf16_f32 v7, v68, v69
	s_waitcnt lgkmcnt(13)
	v_mfma_f32_32x32x16_bf16 v[114:129], v[142:145], v[154:157], v[114:129]
	ds_read_b64_tr_b16 v[66:67], v190 offset:30720
	ds_read_b64_tr_b16 v[68:69], v190 offset:31232
	v_add_f32_e32 v2, v72, v2
	v_add_f32_e32 v2, v73, v2
	v_add_f32_e32 v2, v74, v2
	v_add_f32_e32 v2, v75, v2
	v_cvt_pk_bf16_f32 v8, v70, v71
	v_cvt_pk_bf16_f32 v9, v72, v73
	s_waitcnt lgkmcnt(14)
	v_mfma_f32_32x32x16_bf16 v[98:113], v[138:141], v[154:157], v[98:113]
	ds_read_b64_tr_b16 v[70:71], v190 offset:27648
	ds_read_b64_tr_b16 v[72:73], v190 offset:28160
	v_add_f32_e32 v2, v76, v2
	v_add_f32_e32 v2, v77, v2
	v_add_f32_e32 v2, v78, v2
	v_add_f32_e32 v94, v79, v2
	v_cvt_pk_bf16_f32 v2, v74, v75
	v_cvt_pk_bf16_f32 v3, v76, v77
	s_waitcnt lgkmcnt(14)
	v_mfma_f32_32x32x16_bf16 v[114:129], v[134:137], v[150:153], v[114:129]
	ds_read_b64_tr_b16 v[74:75], v190 offset:31744
	ds_read_b64_tr_b16 v[76:77], v190 offset:32256
	v_add_f32_e32 v4, v80, v94
	v_add_f32_e32 v4, v81, v4
	v_add_f32_e32 v94, 0, v4
	v_cvt_pk_bf16_f32 v4, v78, v79
	v_cvt_pk_bf16_f32 v5, v80, v81
	v_mfma_f32_32x32x16_bf16 v[98:113], v[130:133], v[150:153], v[98:113]
	s_add_u32 s16, s14, 0x2490000
	s_addc_u32 s17, s15, 0
	s_cmp_lg_u32 0, -1
	s_cselect_b32 s23, 0, 0
	s_add_i32 s22, s23, s21
	s_add_i32 s24, s22, 0x2000
	s_mov_b32 s25, m0
	s_mov_b32 m0, s24
	s_nop 0
	global_load_lds_dwordx4 v193, s[16:17]
	s_mov_b32 m0, s25
	s_add_u32 s24, s12, 0x2400000
	s_addc_u32 s25, s13, 0
	s_add_i32 s16, s23, 0xa000
	s_add_i32 s17, s21, s16
	s_mov_b32 s21, m0
	s_mov_b32 m0, s17
	s_nop 0
	global_load_lds_dwordx4 v192, s[24:25]
	s_mov_b32 m0, s21
	v_add_f32_e32 v194, v194, v94
	s_waitcnt lgkmcnt(14)
	v_mfma_f32_32x32x16_bf16 v[18:33], v[146:149], v[182:185], v[18:33]
	v_exp_f32_e32 v114, v114
	v_exp_f32_e32 v115, v115
	v_exp_f32_e32 v116, v116
	v_exp_f32_e32 v117, v117
	s_waitcnt lgkmcnt(12)
; #define WAIT_BAR(N) asm volatile("s_waitcnt vmcnt(" #N ") lgkmcnt(0)\n\ts_barrier" ::: "memory")
; #define RESC() do { if (resc) { asm volatile("s_waitcnt lgkmcnt(0)" ::: "memory"); \
;       _Pragma("unroll") for (int d_ = 0; d_ < 2; ++d_) _Pragma("unroll") for (int r = 0; r < 16; ++r) o[d_][r] *= wsf[crow(r, hi)]; } } while (0)
; #define ROT() do { sl_prev = sl_cur; sl_cur = sl_next; sl_next = (sl_next == (NSLOT - 1) * SLOTB) ? 0 : sl_next + SLOTB; } while (0)
; #define ENDW(tt) do { if ((tt) + 3 < NT) { WAIT_BAR(2); } else if ((tt) + 2 < NT) { WAIT_BAR(1); } else { WAIT_BAR(0); } } while (0)
;     ...
;     int t = 1;
;     for (; t + 5 < NT; t += 2) {
;         STEP(pB0, pB1, pA0, pA1, t, true, true, true);     WAIT_BAR(2); RESC(); ROT();
;         STEP(pA0, pA1, pB0, pB1, t + 1, true, true, true); WAIT_BAR(2); RESC(); ROT();
;     }
;     ...
;     for (; t + 1 < NT; t += 2) {
;         STEP(pB0, pB1, pA0, pA1, t, (t + 3 < NT), (t + 1 < NT), (t + 1 < NT));         ENDW(t);     RESC(); ROT();
;         STEP(pA0, pA1, pB0, pB1, t + 1, (t + 4 < NT), (t + 2 < NT), (t + 2 < NT));     ENDW(t + 1); RESC(); ROT();
	v_mfma_f32_32x32x16_bf16 v[34:49], v[146:149], v[178:181], v[34:49]
	v_exp_f32_e32 v118, v118
	v_exp_f32_e32 v119, v119
	v_exp_f32_e32 v120, v120
	v_exp_f32_e32 v121, v121
	ds_read_b128 v[78:81], v191 offset:16384
	ds_read_b128 v[94:97], v191 offset:16896
	s_waitcnt lgkmcnt(12)
	v_mfma_f32_32x32x16_bf16 v[18:33], v[10:13], v[82:85], v[18:33]
	v_exp_f32_e32 v122, v122
	v_exp_f32_e32 v123, v123
	v_exp_f32_e32 v124, v124
	v_exp_f32_e32 v125, v125
	ds_read_b128 v[166:169], v191 offset:18432
	ds_read_b128 v[170:173], v191 offset:18944
	s_waitcnt lgkmcnt(12)
	v_mfma_f32_32x32x16_bf16 v[34:49], v[10:13], v[86:89], v[34:49]
	v_exp_f32_e32 v126, v126
	v_exp_f32_e32 v127, v127
	v_exp_f32_e32 v128, v128
	v_exp_f32_e32 v129, v129
	ds_read_b128 v[174:177], v191 offset:20480
	ds_read_b128 v[178:181], v191 offset:20992
	s_waitcnt lgkmcnt(12)
	v_mfma_f32_32x32x16_bf16 v[18:33], v[6:9], v[90:93], v[18:33]
	v_exp_f32_e32 v98, v98
	v_exp_f32_e32 v99, v99
	v_exp_f32_e32 v100, v100
	v_exp_f32_e32 v101, v101
	ds_read_b128 v[90:93], v191 offset:22528
	ds_read_b128 v[82:85], v191 offset:23040
	s_waitcnt lgkmcnt(12)
	v_mfma_f32_32x32x16_bf16 v[34:49], v[6:9], v[66:69], v[34:49]
	v_exp_f32_e32 v102, v102
	v_exp_f32_e32 v103, v103
	v_exp_f32_e32 v104, v104
	v_exp_f32_e32 v105, v105
	s_waitcnt lgkmcnt(10)
	v_mfma_f32_32x32x16_bf16 v[18:33], v[2:5], v[70:73], v[18:33]
	v_exp_f32_e32 v106, v106
	v_exp_f32_e32 v107, v107
	v_exp_f32_e32 v108, v108
	v_exp_f32_e32 v109, v109
	s_waitcnt lgkmcnt(8)
	v_mfma_f32_32x32x16_bf16 v[34:49], v[2:5], v[74:77], v[34:49]
	v_exp_f32_e32 v110, v110
	v_exp_f32_e32 v111, v111
	v_exp_f32_e32 v112, v112
	v_exp_f32_e32 v113, v113
	s_waitcnt vmcnt(2) lgkmcnt(0)
	s_barrier
	ds_read_b64_tr_b16 v[182:183], v190 offset:32768
	ds_read_b64_tr_b16 v[184:185], v190 offset:33280
	v_add_f32_e32 v2, v114, v115
	v_add_f32_e32 v2, v116, v2
	v_add_f32_e32 v2, v117, v2
	v_add_f32_e32 v2, v118, v2
	v_add_f32_e32 v2, v119, v2
	v_cvt_pk_bf16_f32 v146, v114, v115
	v_cvt_pk_bf16_f32 v147, v116, v117
	s_waitcnt lgkmcnt(9)
	v_mfma_f32_32x32x16_bf16 v[130:145], v[78:81], v[162:165], v[50:65]
	ds_read_b64_tr_b16 v[114:115], v190 offset:36864
	ds_read_b64_tr_b16 v[116:117], v190 offset:37376
	s_waitcnt lgkmcnt(10)
	v_mfma_f32_32x32x16_bf16 v[66:81], v[94:97], v[162:165], v[50:65]
	v_add_f32_e32 v2, v120, v2
	v_add_f32_e32 v2, v121, v2
	v_add_f32_e32 v2, v122, v2
	v_add_f32_e32 v2, v123, v2
	v_cvt_pk_bf16_f32 v148, v118, v119
	v_cvt_pk_bf16_f32 v149, v120, v121
	ds_read_b64_tr_b16 v[86:87], v190 offset:33792
	ds_read_b64_tr_b16 v[88:89], v190 offset:34304
	v_add_f32_e32 v2, v124, v2
	v_add_f32_e32 v2, v125, v2
	v_add_f32_e32 v2, v126, v2
	v_add_f32_e32 v2, v127, v2
	v_cvt_pk_bf16_f32 v10, v122, v123
	v_cvt_pk_bf16_f32 v11, v124, v125
	s_waitcnt lgkmcnt(11)
	v_mfma_f32_32x32x16_bf16 v[130:145], v[166:169], v[158:161], v[130:145]
	ds_read_b64_tr_b16 v[94:95], v190 offset:37888
	ds_read_b64_tr_b16 v[96:97], v190 offset:38400
	s_waitcnt lgkmcnt(12)
	v_mfma_f32_32x32x16_bf16 v[66:81], v[170:173], v[158:161], v[66:81]
	v_add_f32_e32 v2, v128, v2
	v_add_f32_e32 v2, v129, v2
	v_add_f32_e32 v2, v98, v2
	v_add_f32_e32 v2, v99, v2
	v_cvt_pk_bf16_f32 v12, v126, v127
	v_cvt_pk_bf16_f32 v13, v128, v129
	ds_read_b64_tr_b16 v[118:119], v190 offset:34816
	ds_read_b64_tr_b16 v[120:121], v190 offset:35328
	v_add_f32_e32 v2, v100, v2
	v_add_f32_e32 v2, v101, v2
	v_add_f32_e32 v2, v102, v2
	v_add_f32_e32 v2, v103, v2
	v_cvt_pk_bf16_f32 v6, v98, v99
	v_cvt_pk_bf16_f32 v7, v100, v101
	s_waitcnt lgkmcnt(13)
	v_mfma_f32_32x32x16_bf16 v[130:145], v[174:177], v[154:157], v[130:145]
	ds_read_b64_tr_b16 v[122:123], v190 offset:38912
	ds_read_b64_tr_b16 v[124:125], v190 offset:39424
	s_waitcnt lgkmcnt(14)
	v_mfma_f32_32x32x16_bf16 v[66:81], v[178:181], v[154:157], v[66:81]
	v_add_f32_e32 v2, v104, v2
	v_add_f32_e32 v2, v105, v2
	v_add_f32_e32 v2, v106, v2
	v_add_f32_e32 v2, v107, v2
	v_cvt_pk_bf16_f32 v8, v102, v103
	v_cvt_pk_bf16_f32 v9, v104, v105
	ds_read_b64_tr_b16 v[102:103], v190 offset:35840
	ds_read_b64_tr_b16 v[104:105], v190 offset:36352
	v_add_f32_e32 v2, v108, v2
	v_add_f32_e32 v2, v109, v2
	v_add_f32_e32 v2, v110, v2
	v_add_f32_e32 v98, v111, v2
	v_cvt_pk_bf16_f32 v2, v106, v107
	v_cvt_pk_bf16_f32 v3, v108, v109
	s_waitcnt lgkmcnt(14)
	v_mfma_f32_32x32x16_bf16 v[130:145], v[90:93], v[150:153], v[130:145]
	ds_read_b64_tr_b16 v[90:91], v190 offset:39936
	ds_read_b64_tr_b16 v[92:93], v190 offset:40448
	v_mfma_f32_32x32x16_bf16 v[66:81], v[82:85], v[150:153], v[66:81]
	v_add_f32_e32 v4, v112, v98
	v_add_f32_e32 v4, v113, v4
	v_add_f32_e32 v82, 0, v4
	v_cvt_pk_bf16_f32 v4, v110, v111
	v_cvt_pk_bf16_f32 v5, v112, v113
	s_add_u32 s14, s14, 0x24d8000
	s_addc_u32 s15, s15, 0
	s_add_i32 s21, s22, 0x4000
	s_mov_b32 s23, m0
	s_mov_b32 m0, s21
	s_nop 0
	global_load_lds_dwordx4 v193, s[14:15]
	s_mov_b32 m0, s23
	s_add_u32 s14, s12, 0x2448000
	s_addc_u32 s15, s13, 0
	s_mov_b32 s21, m0
	s_mov_b32 m0, s20
	s_nop 0
	global_load_lds_dwordx4 v192, s[14:15]
	s_mov_b32 m0, s21
	v_add_f32_e32 v194, v194, v82
	s_waitcnt lgkmcnt(14)
	v_mfma_f32_32x32x16_bf16 v[18:33], v[146:149], v[182:185], v[18:33]
	v_exp_f32_e32 v130, v130
	v_exp_f32_e32 v131, v131
	v_exp_f32_e32 v132, v132
	v_exp_f32_e32 v133, v133
	s_waitcnt lgkmcnt(12)
	v_mfma_f32_32x32x16_bf16 v[34:49], v[146:149], v[114:117], v[34:49]
	v_exp_f32_e32 v134, v134
	v_exp_f32_e32 v135, v135
	v_exp_f32_e32 v136, v136
	v_exp_f32_e32 v137, v137
	ds_read_b128 v[82:85], v191
	ds_read_b128 v[106:109], v191 offset:512
	s_waitcnt lgkmcnt(12)
	v_mfma_f32_32x32x16_bf16 v[18:33], v[10:13], v[86:89], v[18:33]
	v_exp_f32_e32 v138, v138
	v_exp_f32_e32 v139, v139
	v_exp_f32_e32 v140, v140
	v_exp_f32_e32 v141, v141
	ds_read_b128 v[110:113], v191 offset:2048
	ds_read_b128 v[166:169], v191 offset:2560
	s_waitcnt lgkmcnt(12)
	v_mfma_f32_32x32x16_bf16 v[34:49], v[10:13], v[94:97], v[34:49]
	v_exp_f32_e32 v142, v142
	v_exp_f32_e32 v143, v143
	v_exp_f32_e32 v144, v144
	v_exp_f32_e32 v145, v145
	ds_read_b128 v[170:173], v191 offset:4096
	ds_read_b128 v[174:177], v191 offset:4608
	s_waitcnt lgkmcnt(12)
	v_mfma_f32_32x32x16_bf16 v[18:33], v[6:9], v[118:121], v[18:33]
	v_exp_f32_e32 v66, v66
	v_exp_f32_e32 v67, v67
	v_exp_f32_e32 v68, v68
	v_exp_f32_e32 v69, v69
	ds_read_b128 v[178:181], v191 offset:6144
	ds_read_b128 v[98:101], v191 offset:6656
	s_waitcnt lgkmcnt(12)
	v_mfma_f32_32x32x16_bf16 v[34:49], v[6:9], v[122:125], v[34:49]
	v_exp_f32_e32 v70, v70
	v_exp_f32_e32 v71, v71
	v_exp_f32_e32 v72, v72
	v_exp_f32_e32 v73, v73
	s_waitcnt lgkmcnt(10)
	v_mfma_f32_32x32x16_bf16 v[18:33], v[2:5], v[102:105], v[18:33]
	v_exp_f32_e32 v74, v74
	v_exp_f32_e32 v75, v75
	v_exp_f32_e32 v76, v76
	v_exp_f32_e32 v77, v77
	s_waitcnt lgkmcnt(8)
	v_mfma_f32_32x32x16_bf16 v[34:49], v[2:5], v[90:93], v[34:49]
	v_exp_f32_e32 v78, v78
	v_exp_f32_e32 v79, v79
	v_exp_f32_e32 v80, v80
	v_exp_f32_e32 v81, v81
	s_waitcnt vmcnt(2) lgkmcnt(0)
	s_barrier
; #define WAIT_BAR(N) asm volatile("s_waitcnt vmcnt(" #N ") lgkmcnt(0)\n\ts_barrier" ::: "memory")
; #define RESC() do { if (resc) { asm volatile("s_waitcnt lgkmcnt(0)" ::: "memory"); \
;       _Pragma("unroll") for (int d_ = 0; d_ < 2; ++d_) _Pragma("unroll") for (int r = 0; r < 16; ++r) o[d_][r] *= wsf[crow(r, hi)]; } } while (0)
; #define ROT() do { sl_prev = sl_cur; sl_cur = sl_next; sl_next = (sl_next == (NSLOT - 1) * SLOTB) ? 0 : sl_next + SLOTB; } while (0)
; #define ENDW(tt) do { if ((tt) + 3 < NT) { WAIT_BAR(2); } else if ((tt) + 2 < NT) { WAIT_BAR(1); } else { WAIT_BAR(0); } } while (0)
;     ...
;     int t = 1;
;     for (; t + 5 < NT; t += 2) {
;         STEP(pB0, pB1, pA0, pA1, t, true, true, true);     WAIT_BAR(2); RESC(); ROT();
;         STEP(pA0, pA1, pB0, pB1, t + 1, true, true, true); WAIT_BAR(2); RESC(); ROT();
;     }
;     ...
;     for (; t + 1 < NT; t += 2) {
;         STEP(pB0, pB1, pA0, pA1, t, (t + 3 < NT), (t + 1 < NT), (t + 1 < NT));         ENDW(t);     RESC(); ROT();
;         STEP(pA0, pA1, pB0, pB1, t + 1, (t + 4 < NT), (t + 2 < NT), (t + 2 < NT));     ENDW(t + 1); RESC(); ROT();
	ds_read_b64_tr_b16 v[102:103], v190 offset:40960
	ds_read_b64_tr_b16 v[104:105], v190 offset:41472
	v_add_f32_e32 v2, v130, v131
	v_add_f32_e32 v2, v132, v2
	v_add_f32_e32 v2, v133, v2
	v_add_f32_e32 v2, v134, v2
	v_add_f32_e32 v2, v135, v2
	v_cvt_pk_bf16_f32 v146, v130, v131
	v_cvt_pk_bf16_f32 v147, v132, v133
	s_waitcnt lgkmcnt(9)
	v_mfma_f32_32x32x16_bf16 v[114:129], v[82:85], v[162:165], v[50:65]
	ds_read_b64_tr_b16 v[130:131], v190 offset:45056
	ds_read_b64_tr_b16 v[132:133], v190 offset:45568
	v_add_f32_e32 v2, v136, v2
	v_add_f32_e32 v2, v137, v2
	v_add_f32_e32 v2, v138, v2
	v_add_f32_e32 v2, v139, v2
	v_cvt_pk_bf16_f32 v148, v134, v135
	v_cvt_pk_bf16_f32 v149, v136, v137
	s_waitcnt lgkmcnt(10)
	v_mfma_f32_32x32x16_bf16 v[82:97], v[106:109], v[162:165], v[50:65]
	ds_read_b64_tr_b16 v[106:107], v190 offset:41984
	ds_read_b64_tr_b16 v[108:109], v190 offset:42496
	v_add_f32_e32 v2, v140, v2
	v_add_f32_e32 v2, v141, v2
	v_add_f32_e32 v2, v142, v2
	v_add_f32_e32 v2, v143, v2
	v_cvt_pk_bf16_f32 v10, v138, v139
	v_cvt_pk_bf16_f32 v11, v140, v141
	s_waitcnt lgkmcnt(11)
	v_mfma_f32_32x32x16_bf16 v[114:129], v[110:113], v[158:161], v[114:129]
	ds_read_b64_tr_b16 v[110:111], v190 offset:46080
	ds_read_b64_tr_b16 v[112:113], v190 offset:46592
	v_add_f32_e32 v2, v144, v2
	v_add_f32_e32 v2, v145, v2
	v_add_f32_e32 v2, v66, v2
	v_add_f32_e32 v2, v67, v2
	v_cvt_pk_bf16_f32 v12, v142, v143
	v_cvt_pk_bf16_f32 v13, v144, v145
	s_waitcnt lgkmcnt(12)
	v_mfma_f32_32x32x16_bf16 v[82:97], v[166:169], v[158:161], v[82:97]
	ds_read_b64_tr_b16 v[134:135], v190 offset:43008
	ds_read_b64_tr_b16 v[136:137], v190 offset:43520
	v_add_f32_e32 v2, v68, v2
	v_add_f32_e32 v2, v69, v2
	v_add_f32_e32 v2, v70, v2
	v_add_f32_e32 v2, v71, v2
	v_cvt_pk_bf16_f32 v6, v66, v67
	v_cvt_pk_bf16_f32 v7, v68, v69
	s_waitcnt lgkmcnt(13)
	v_mfma_f32_32x32x16_bf16 v[114:129], v[170:173], v[154:157], v[114:129]
	ds_read_b64_tr_b16 v[66:67], v190 offset:47104
	ds_read_b64_tr_b16 v[68:69], v190 offset:47616
	v_add_f32_e32 v2, v72, v2
	v_add_f32_e32 v2, v73, v2
	v_add_f32_e32 v2, v74, v2
	v_add_f32_e32 v2, v75, v2
	v_cvt_pk_bf16_f32 v8, v70, v71
	v_cvt_pk_bf16_f32 v9, v72, v73
	s_waitcnt lgkmcnt(14)
	v_mfma_f32_32x32x16_bf16 v[82:97], v[174:177], v[154:157], v[82:97]
	ds_read_b64_tr_b16 v[70:71], v190 offset:44032
	ds_read_b64_tr_b16 v[72:73], v190 offset:44544
	v_add_f32_e32 v2, v76, v2
	v_add_f32_e32 v2, v77, v2
	v_add_f32_e32 v2, v78, v2
	v_add_f32_e32 v138, v79, v2
	v_cvt_pk_bf16_f32 v2, v74, v75
	v_cvt_pk_bf16_f32 v3, v76, v77
	s_waitcnt lgkmcnt(14)
	v_mfma_f32_32x32x16_bf16 v[114:129], v[178:181], v[150:153], v[114:129]
	ds_read_b64_tr_b16 v[74:75], v190 offset:48128
	ds_read_b64_tr_b16 v[76:77], v190 offset:48640
	v_add_f32_e32 v4, v80, v138
	v_add_f32_e32 v4, v81, v4
	v_mfma_f32_32x32x16_bf16 v[82:97], v[98:101], v[150:153], v[82:97]
	v_add_f32_e32 v98, 0, v4
	v_cvt_pk_bf16_f32 v4, v78, v79
	v_cvt_pk_bf16_f32 v5, v80, v81
	s_add_u32 s14, s12, 0x2490000
	s_addc_u32 s15, s13, 0
	s_add_i32 s22, s22, 0x8000
	s_mov_b32 s20, m0
	s_mov_b32 m0, s22
	s_nop 0
	global_load_lds_dwordx4 v192, s[14:15]
	s_mov_b32 m0, s20
	v_add_f32_e32 v182, v194, v98
	s_waitcnt lgkmcnt(14)
	v_mfma_f32_32x32x16_bf16 v[18:33], v[146:149], v[102:105], v[18:33]
	v_exp_f32_e32 v114, v114
	v_exp_f32_e32 v115, v115
	v_exp_f32_e32 v116, v116
	v_exp_f32_e32 v117, v117
	s_waitcnt lgkmcnt(12)
	v_mfma_f32_32x32x16_bf16 v[34:49], v[146:149], v[130:133], v[34:49]
	v_exp_f32_e32 v118, v118
	v_exp_f32_e32 v119, v119
	v_exp_f32_e32 v120, v120
	v_exp_f32_e32 v121, v121
	ds_read_b128 v[78:81], v191 offset:8192
	ds_read_b128 v[138:141], v191 offset:8704
	s_waitcnt lgkmcnt(12)
	v_mfma_f32_32x32x16_bf16 v[18:33], v[10:13], v[106:109], v[18:33]
	v_exp_f32_e32 v122, v122
	v_exp_f32_e32 v123, v123
	v_exp_f32_e32 v124, v124
	v_exp_f32_e32 v125, v125
	ds_read_b128 v[142:145], v191 offset:10240
	ds_read_b128 v[166:169], v191 offset:10752
	s_waitcnt lgkmcnt(12)
	v_mfma_f32_32x32x16_bf16 v[34:49], v[10:13], v[110:113], v[34:49]
	v_exp_f32_e32 v126, v126
	v_exp_f32_e32 v127, v127
	v_exp_f32_e32 v128, v128
	v_exp_f32_e32 v129, v129
	ds_read_b128 v[170:173], v191 offset:12288
	ds_read_b128 v[174:177], v191 offset:12800
	s_waitcnt lgkmcnt(12)
	v_mfma_f32_32x32x16_bf16 v[18:33], v[6:9], v[134:137], v[18:33]
	v_exp_f32_e32 v82, v82
	v_exp_f32_e32 v83, v83
	v_exp_f32_e32 v84, v84
	v_exp_f32_e32 v85, v85
	ds_read_b128 v[134:137], v191 offset:14336
	ds_read_b128 v[130:133], v191 offset:14848
	s_waitcnt lgkmcnt(12)
	v_mfma_f32_32x32x16_bf16 v[34:49], v[6:9], v[66:69], v[34:49]
	v_exp_f32_e32 v86, v86
	v_exp_f32_e32 v87, v87
	v_exp_f32_e32 v88, v88
	v_exp_f32_e32 v89, v89
	s_waitcnt lgkmcnt(10)
	v_mfma_f32_32x32x16_bf16 v[18:33], v[2:5], v[70:73], v[18:33]
	v_exp_f32_e32 v90, v90
	v_exp_f32_e32 v91, v91
	v_exp_f32_e32 v92, v92
	v_exp_f32_e32 v93, v93
	s_waitcnt lgkmcnt(8)
	v_mfma_f32_32x32x16_bf16 v[34:49], v[2:5], v[74:77], v[34:49]
	v_exp_f32_e32 v94, v94
	v_exp_f32_e32 v95, v95
	v_exp_f32_e32 v96, v96
	v_exp_f32_e32 v97, v97
	s_waitcnt vmcnt(1) lgkmcnt(0)
	s_barrier
; #define WAIT_BAR(N) asm volatile("s_waitcnt vmcnt(" #N ") lgkmcnt(0)\n\ts_barrier" ::: "memory")
; #define RESC() do { if (resc) { asm volatile("s_waitcnt lgkmcnt(0)" ::: "memory"); \
;       _Pragma("unroll") for (int d_ = 0; d_ < 2; ++d_) _Pragma("unroll") for (int r = 0; r < 16; ++r) o[d_][r] *= wsf[crow(r, hi)]; } } while (0)
; #define ROT() do { sl_prev = sl_cur; sl_cur = sl_next; sl_next = (sl_next == (NSLOT - 1) * SLOTB) ? 0 : sl_next + SLOTB; } while (0)
; #define ENDW(tt) do { if ((tt) + 3 < NT) { WAIT_BAR(2); } else if ((tt) + 2 < NT) { WAIT_BAR(1); } else { WAIT_BAR(0); } } while (0)
;     ...
;     int t = 1;
;     for (; t + 5 < NT; t += 2) {
;         STEP(pB0, pB1, pA0, pA1, t, true, true, true);     WAIT_BAR(2); RESC(); ROT();
;         STEP(pA0, pA1, pB0, pB1, t + 1, true, true, true); WAIT_BAR(2); RESC(); ROT();
;     }
;     ...
;     for (; t + 1 < NT; t += 2) {
;         STEP(pB0, pB1, pA0, pA1, t, (t + 3 < NT), (t + 1 < NT), (t + 1 < NT));         ENDW(t);     RESC(); ROT();
;         STEP(pA0, pA1, pB0, pB1, t + 1, (t + 4 < NT), (t + 2 < NT), (t + 2 < NT));     ENDW(t + 1); RESC(); ROT();
	ds_read_b64_tr_b16 v[178:179], v190 offset:24576
	ds_read_b64_tr_b16 v[180:181], v190 offset:25088
	v_add_f32_e32 v2, v114, v115
	v_add_f32_e32 v2, v116, v2
	v_add_f32_e32 v2, v117, v2
	v_add_f32_e32 v2, v118, v2
	v_add_f32_e32 v2, v119, v2
	v_cvt_pk_bf16_f32 v146, v114, v115
	v_cvt_pk_bf16_f32 v147, v116, v117
	s_waitcnt lgkmcnt(9)
	v_mfma_f32_32x32x16_bf16 v[98:113], v[78:81], v[162:165], v[50:65]
	ds_read_b64_tr_b16 v[114:115], v190 offset:28672
	ds_read_b64_tr_b16 v[116:117], v190 offset:29184
	s_waitcnt lgkmcnt(10)
	v_mfma_f32_32x32x16_bf16 v[66:81], v[138:141], v[162:165], v[50:65]
	v_add_f32_e32 v2, v120, v2
	v_add_f32_e32 v2, v121, v2
	v_add_f32_e32 v2, v122, v2
	v_add_f32_e32 v2, v123, v2
	v_cvt_pk_bf16_f32 v148, v118, v119
	v_cvt_pk_bf16_f32 v149, v120, v121
	ds_read_b64_tr_b16 v[118:119], v190 offset:25600
	ds_read_b64_tr_b16 v[120:121], v190 offset:26112
	v_add_f32_e32 v2, v124, v2
	v_add_f32_e32 v2, v125, v2
	v_add_f32_e32 v2, v126, v2
	v_add_f32_e32 v2, v127, v2
	v_cvt_pk_bf16_f32 v10, v122, v123
	v_cvt_pk_bf16_f32 v11, v124, v125
	s_waitcnt lgkmcnt(11)
	v_mfma_f32_32x32x16_bf16 v[98:113], v[142:145], v[158:161], v[98:113]
	ds_read_b64_tr_b16 v[122:123], v190 offset:29696
	ds_read_b64_tr_b16 v[124:125], v190 offset:30208
	s_waitcnt lgkmcnt(12)
	v_mfma_f32_32x32x16_bf16 v[66:81], v[166:169], v[158:161], v[66:81]
	v_add_f32_e32 v2, v128, v2
	v_add_f32_e32 v2, v129, v2
	v_add_f32_e32 v2, v82, v2
	v_add_f32_e32 v2, v83, v2
	v_cvt_pk_bf16_f32 v12, v126, v127
	v_cvt_pk_bf16_f32 v13, v128, v129
	ds_read_b64_tr_b16 v[138:139], v190 offset:26624
	ds_read_b64_tr_b16 v[140:141], v190 offset:27136
	v_add_f32_e32 v2, v84, v2
	v_add_f32_e32 v2, v85, v2
	v_add_f32_e32 v2, v86, v2
	v_add_f32_e32 v2, v87, v2
	v_cvt_pk_bf16_f32 v6, v82, v83
	v_cvt_pk_bf16_f32 v7, v84, v85
	s_waitcnt lgkmcnt(13)
	v_mfma_f32_32x32x16_bf16 v[98:113], v[170:173], v[154:157], v[98:113]
	ds_read_b64_tr_b16 v[82:83], v190 offset:30720
	ds_read_b64_tr_b16 v[84:85], v190 offset:31232
	s_waitcnt lgkmcnt(14)
	v_mfma_f32_32x32x16_bf16 v[66:81], v[174:177], v[154:157], v[66:81]
	v_add_f32_e32 v2, v88, v2
	v_add_f32_e32 v2, v89, v2
	v_add_f32_e32 v2, v90, v2
	v_add_f32_e32 v2, v91, v2
	v_cvt_pk_bf16_f32 v8, v86, v87
	v_cvt_pk_bf16_f32 v9, v88, v89
	ds_read_b64_tr_b16 v[86:87], v190 offset:27648
	ds_read_b64_tr_b16 v[88:89], v190 offset:28160
	v_add_f32_e32 v2, v92, v2
	v_add_f32_e32 v2, v93, v2
	v_add_f32_e32 v2, v94, v2
	v_add_f32_e32 v126, v95, v2
	v_cvt_pk_bf16_f32 v2, v90, v91
	v_cvt_pk_bf16_f32 v3, v92, v93
	s_waitcnt lgkmcnt(14)
	v_mfma_f32_32x32x16_bf16 v[98:113], v[134:137], v[150:153], v[98:113]
	ds_read_b64_tr_b16 v[90:91], v190 offset:31744
	ds_read_b64_tr_b16 v[92:93], v190 offset:32256
	v_mfma_f32_32x32x16_bf16 v[66:81], v[130:133], v[150:153], v[66:81]
	v_add_f32_e32 v4, v96, v126
	v_add_f32_e32 v4, v97, v4
	v_add_f32_e32 v126, 0, v4
	v_cvt_pk_bf16_f32 v4, v94, v95
	v_cvt_pk_bf16_f32 v5, v96, v97
	s_add_u32 s12, s12, 0x24d8000
	s_addc_u32 s13, s13, 0
	s_mov_b32 s14, m0
	s_mov_b32 m0, s17
	s_nop 0
	global_load_lds_dwordx4 v192, s[12:13]
	s_mov_b32 m0, s14
	v_add_f32_e32 v126, v182, v126
	s_waitcnt lgkmcnt(14)
	v_mfma_f32_32x32x16_bf16 v[18:33], v[146:149], v[178:181], v[18:33]
	v_exp_f32_e32 v98, v98
	v_exp_f32_e32 v99, v99
	v_exp_f32_e32 v100, v100
	v_exp_f32_e32 v101, v101
	s_waitcnt lgkmcnt(12)
	v_mfma_f32_32x32x16_bf16 v[34:49], v[146:149], v[114:117], v[34:49]
	v_exp_f32_e32 v102, v102
	v_exp_f32_e32 v103, v103
	v_exp_f32_e32 v104, v104
	v_exp_f32_e32 v105, v105
	ds_read_b128 v[128:131], v191 offset:16384
	ds_read_b128 v[132:135], v191 offset:16896
	s_waitcnt lgkmcnt(12)
	v_mfma_f32_32x32x16_bf16 v[18:33], v[10:13], v[118:121], v[18:33]
	v_exp_f32_e32 v106, v106
	v_exp_f32_e32 v107, v107
	v_exp_f32_e32 v108, v108
	v_exp_f32_e32 v109, v109
	ds_read_b128 v[142:145], v191 offset:18432
	ds_read_b128 v[166:169], v191 offset:18944
	s_waitcnt lgkmcnt(12)
	v_mfma_f32_32x32x16_bf16 v[34:49], v[10:13], v[122:125], v[34:49]
	v_exp_f32_e32 v110, v110
	v_exp_f32_e32 v111, v111
	v_exp_f32_e32 v112, v112
	v_exp_f32_e32 v113, v113
	ds_read_b128 v[170:173], v191 offset:20480
	ds_read_b128 v[174:177], v191 offset:20992
	s_waitcnt lgkmcnt(12)
	v_mfma_f32_32x32x16_bf16 v[18:33], v[6:9], v[138:141], v[18:33]
	v_exp_f32_e32 v66, v66
	v_exp_f32_e32 v67, v67
	v_exp_f32_e32 v68, v68
	v_exp_f32_e32 v69, v69
	ds_read_b128 v[136:139], v191 offset:22528
	ds_read_b128 v[122:125], v191 offset:23040
	s_waitcnt lgkmcnt(12)
	v_mfma_f32_32x32x16_bf16 v[34:49], v[6:9], v[82:85], v[34:49]
	v_exp_f32_e32 v70, v70
	v_exp_f32_e32 v71, v71
	v_exp_f32_e32 v72, v72
	v_exp_f32_e32 v73, v73
	s_waitcnt lgkmcnt(10)
	v_mfma_f32_32x32x16_bf16 v[18:33], v[2:5], v[86:89], v[18:33]
	v_exp_f32_e32 v74, v74
	v_exp_f32_e32 v75, v75
	v_exp_f32_e32 v76, v76
	v_exp_f32_e32 v77, v77
	s_waitcnt lgkmcnt(8)
	v_mfma_f32_32x32x16_bf16 v[34:49], v[2:5], v[90:93], v[34:49]
	v_exp_f32_e32 v78, v78
	v_exp_f32_e32 v79, v79
	v_exp_f32_e32 v80, v80
	v_exp_f32_e32 v81, v81
	s_waitcnt vmcnt(0) lgkmcnt(0)
	s_barrier
; #define WAIT_BAR(N) asm volatile("s_waitcnt vmcnt(" #N ") lgkmcnt(0)\n\ts_barrier" ::: "memory")
; #define RESC() do { if (resc) { asm volatile("s_waitcnt lgkmcnt(0)" ::: "memory"); \
;       _Pragma("unroll") for (int d_ = 0; d_ < 2; ++d_) _Pragma("unroll") for (int r = 0; r < 16; ++r) o[d_][r] *= wsf[crow(r, hi)]; } } while (0)
; #define ROT() do { sl_prev = sl_cur; sl_cur = sl_next; sl_next = (sl_next == (NSLOT - 1) * SLOTB) ? 0 : sl_next + SLOTB; } while (0)
; #define PKW(P, B) cvtpk_s(P[B], P[B + 1])
; #define ENDW(tt) do { if ((tt) + 3 < NT) { WAIT_BAR(2); } else if ((tt) + 2 < NT) { WAIT_BAR(1); } else { WAIT_BAR(0); } } while (0)
;     ...
;     int t = 1;
;     for (; t + 5 < NT; t += 2) {
;         STEP(pB0, pB1, pA0, pA1, t, true, true, true);     WAIT_BAR(2); RESC(); ROT();
;         STEP(pA0, pA1, pB0, pB1, t + 1, true, true, true); WAIT_BAR(2); RESC(); ROT();
;     }
;     ...
;     for (; t + 1 < NT; t += 2) {
;         STEP(pB0, pB1, pA0, pA1, t, (t + 3 < NT), (t + 1 < NT), (t + 1 < NT));         ENDW(t);     RESC(); ROT();
;         STEP(pA0, pA1, pB0, pB1, t + 1, (t + 4 < NT), (t + 2 < NT), (t + 2 < NT));     ENDW(t + 1); RESC(); ROT();
;     }
;     STEP(pB0, pB1, pA0, pA1, NT - 1, false, false, false); RESC();
;     { float sacc = pB0[0] + pB0[1]; _Pragma("unroll") for (int r = 2; r < 16; ++r) sacc += pB0[r]; _Pragma("unroll") for (int r = 0; r < 16; ++r) sacc += pB1[r]; l_reg += sacc;
;       pw0 = (u32x4){PKW(pB0, 0), PKW(pB0, 2), PKW(pB0, 4), PKW(pB0, 6)}; pw1 = (u32x4){PKW(pB0, 8), PKW(pB0, 10), PKW(pB0, 12), PKW(pB0, 14)}; pw2 = (u32x4){PKW(pB1, 0), PKW(pB1, 2), PKW(pB1, 4), PKW(pB1, 6)}; pw3 = (u32x4){PKW(pB1, 8), PKW(pB1, 10), PKW(pB1, 12), PKW(pB1, 14)};
	ds_read_b64_tr_b16 v[114:115], v190 offset:32768
	ds_read_b64_tr_b16 v[116:117], v190 offset:33280
	v_add_f32_e32 v2, v98, v99
	v_add_f32_e32 v2, v100, v2
	v_add_f32_e32 v2, v101, v2
	v_add_f32_e32 v2, v102, v2
	v_add_f32_e32 v2, v103, v2
	v_cvt_pk_bf16_f32 v146, v98, v99
	v_cvt_pk_bf16_f32 v147, v100, v101
	s_waitcnt lgkmcnt(9)
	v_mfma_f32_32x32x16_bf16 v[82:97], v[128:131], v[162:165], v[50:65]
	ds_read_b64_tr_b16 v[98:99], v190 offset:36864
	ds_read_b64_tr_b16 v[100:101], v190 offset:37376
	v_add_f32_e32 v2, v104, v2
	v_add_f32_e32 v2, v105, v2
	v_add_f32_e32 v2, v106, v2
	v_add_f32_e32 v2, v107, v2
	v_cvt_pk_bf16_f32 v148, v102, v103
	v_cvt_pk_bf16_f32 v149, v104, v105
	s_waitcnt lgkmcnt(10)
	v_mfma_f32_32x32x16_bf16 v[50:65], v[132:135], v[162:165], v[50:65]
	ds_read_b64_tr_b16 v[118:119], v190 offset:33792
	ds_read_b64_tr_b16 v[120:121], v190 offset:34304
	v_add_f32_e32 v2, v108, v2
	v_add_f32_e32 v2, v109, v2
	v_add_f32_e32 v2, v110, v2
	v_add_f32_e32 v2, v111, v2
	v_cvt_pk_bf16_f32 v10, v106, v107
	v_cvt_pk_bf16_f32 v11, v108, v109
	s_waitcnt lgkmcnt(11)
	v_mfma_f32_32x32x16_bf16 v[82:97], v[142:145], v[158:161], v[82:97]
	ds_read_b64_tr_b16 v[102:103], v190 offset:37888
	ds_read_b64_tr_b16 v[104:105], v190 offset:38400
	v_add_f32_e32 v2, v112, v2
	v_add_f32_e32 v2, v113, v2
	v_add_f32_e32 v2, v66, v2
	v_add_f32_e32 v2, v67, v2
	v_cvt_pk_bf16_f32 v12, v110, v111
	v_cvt_pk_bf16_f32 v13, v112, v113
	s_waitcnt lgkmcnt(12)
	v_mfma_f32_32x32x16_bf16 v[50:65], v[166:169], v[158:161], v[50:65]
	ds_read_b64_tr_b16 v[106:107], v190 offset:34816
	ds_read_b64_tr_b16 v[108:109], v190 offset:35328
	v_add_f32_e32 v2, v68, v2
	v_add_f32_e32 v2, v69, v2
	v_add_f32_e32 v2, v70, v2
	v_add_f32_e32 v2, v71, v2
	v_cvt_pk_bf16_f32 v6, v66, v67
	v_cvt_pk_bf16_f32 v7, v68, v69
	s_waitcnt lgkmcnt(13)
	v_mfma_f32_32x32x16_bf16 v[82:97], v[170:173], v[154:157], v[82:97]
	ds_read_b64_tr_b16 v[66:67], v190 offset:38912
	ds_read_b64_tr_b16 v[68:69], v190 offset:39424
	v_add_f32_e32 v2, v72, v2
	v_add_f32_e32 v2, v73, v2
	v_add_f32_e32 v2, v74, v2
	v_add_f32_e32 v2, v75, v2
	v_cvt_pk_bf16_f32 v8, v70, v71
	v_cvt_pk_bf16_f32 v9, v72, v73
	s_waitcnt lgkmcnt(14)
	v_mfma_f32_32x32x16_bf16 v[50:65], v[174:177], v[154:157], v[50:65]
	ds_read_b64_tr_b16 v[110:111], v190 offset:35840
	ds_read_b64_tr_b16 v[112:113], v190 offset:36352
	v_add_f32_e32 v2, v76, v2
	v_add_f32_e32 v2, v77, v2
	v_add_f32_e32 v2, v78, v2
	v_add_f32_e32 v127, v79, v2
	v_cvt_pk_bf16_f32 v2, v74, v75
	v_cvt_pk_bf16_f32 v3, v76, v77
	s_waitcnt lgkmcnt(14)
	v_mfma_f32_32x32x16_bf16 v[82:97], v[136:139], v[150:153], v[82:97]
	ds_read_b64_tr_b16 v[70:71], v190 offset:39936
	ds_read_b64_tr_b16 v[72:73], v190 offset:40448
	v_add_f32_e32 v4, v80, v127
	v_add_f32_e32 v4, v81, v4
	v_add_f32_e32 v74, 0, v4
	v_cvt_pk_bf16_f32 v4, v78, v79
	v_cvt_pk_bf16_f32 v5, v80, v81
	v_mfma_f32_32x32x16_bf16 v[50:65], v[122:125], v[150:153], v[50:65]
	s_nop 3
	v_exp_f32_e32 v82, v82
	v_exp_f32_e32 v83, v83
	v_exp_f32_e32 v84, v84
	v_exp_f32_e32 v85, v85
	s_nop 0
	v_exp_f32_e32 v86, v86
	v_exp_f32_e32 v87, v87
	v_exp_f32_e32 v88, v88
	v_exp_f32_e32 v89, v89
	s_nop 0
	v_exp_f32_e32 v90, v90
	v_exp_f32_e32 v91, v91
	v_exp_f32_e32 v92, v92
	v_exp_f32_e32 v93, v93
	s_nop 0
	v_exp_f32_e32 v94, v94
	v_exp_f32_e32 v95, v95
	v_exp_f32_e32 v96, v96
	v_exp_f32_e32 v97, v97
	v_exp_f32_e32 v50, v50
	v_exp_f32_e32 v51, v51
	v_exp_f32_e32 v52, v52
	v_exp_f32_e32 v53, v53
	s_nop 0
	v_exp_f32_e32 v54, v54
	v_exp_f32_e32 v55, v55
	v_exp_f32_e32 v56, v56
	v_exp_f32_e32 v57, v57
	s_nop 0
	v_exp_f32_e32 v58, v58
	v_exp_f32_e32 v59, v59
	v_exp_f32_e32 v60, v60
	v_exp_f32_e32 v61, v61
	s_nop 0
	v_exp_f32_e32 v62, v62
	v_exp_f32_e32 v63, v63
	v_exp_f32_e32 v64, v64
	v_exp_f32_e32 v65, v65
	s_waitcnt lgkmcnt(14)
	v_mfma_f32_32x32x16_bf16 v[18:33], v[146:149], v[114:117], v[18:33]
	v_add_f32_e32 v75, v82, v83
	v_add_f32_e32 v75, v84, v75
	v_add_f32_e32 v75, v85, v75
	v_add_f32_e32 v75, v86, v75
	v_add_f32_e32 v75, v87, v75
	v_add_f32_e32 v75, v88, v75
	v_add_f32_e32 v75, v89, v75
	s_waitcnt lgkmcnt(12)
	v_mfma_f32_32x32x16_bf16 v[34:49], v[146:149], v[98:101], v[34:49]
	v_add_f32_e32 v75, v90, v75
	v_add_f32_e32 v75, v91, v75
	v_add_f32_e32 v75, v92, v75
	v_add_f32_e32 v75, v93, v75
	v_add_f32_e32 v75, v94, v75
	v_add_f32_e32 v75, v95, v75
	v_add_f32_e32 v75, v96, v75
	s_waitcnt lgkmcnt(10)
	v_mfma_f32_32x32x16_bf16 v[18:33], v[10:13], v[118:121], v[18:33]
	v_add_f32_e32 v75, v97, v75
	v_add_f32_e32 v75, v50, v75
	v_add_f32_e32 v75, v51, v75
	v_add_f32_e32 v75, v52, v75
	v_add_f32_e32 v75, v53, v75
	v_add_f32_e32 v75, v54, v75
	v_add_f32_e32 v75, v55, v75
	s_waitcnt lgkmcnt(8)
	v_mfma_f32_32x32x16_bf16 v[34:49], v[10:13], v[102:105], v[34:49]
	v_add_f32_e32 v75, v56, v75
	v_add_f32_e32 v75, v57, v75
	v_add_f32_e32 v75, v58, v75
	v_add_f32_e32 v75, v59, v75
	v_add_f32_e32 v75, v60, v75
	v_add_f32_e32 v75, v61, v75
	v_add_f32_e32 v75, v62, v75
	s_waitcnt lgkmcnt(6)
	v_mfma_f32_32x32x16_bf16 v[18:33], v[6:9], v[106:109], v[18:33]
	v_add_f32_e32 v75, v63, v75
	v_add_f32_e32 v75, v64, v75
	v_add_f32_e32 v75, v65, v75
	v_add_f32_e32 v74, v126, v74
	v_add_f32_e32 v74, v74, v75
	v_cvt_pk_bf16_f32 v76, v82, v83
	v_cvt_pk_bf16_f32 v77, v84, v85
	s_waitcnt lgkmcnt(4)
	v_mfma_f32_32x32x16_bf16 v[34:49], v[6:9], v[66:69], v[34:49]
	v_cvt_pk_bf16_f32 v78, v86, v87
	v_cvt_pk_bf16_f32 v79, v88, v89
	v_cvt_pk_bf16_f32 v10, v90, v91
	v_cvt_pk_bf16_f32 v11, v92, v93
	v_cvt_pk_bf16_f32 v12, v94, v95
	v_cvt_pk_bf16_f32 v13, v96, v97
	v_cvt_pk_bf16_f32 v6, v50, v51
	s_waitcnt lgkmcnt(2)
; __device__ __forceinline__ void pv(f32x16* o, int vb, bf16x8 pa0, bf16x8 pa1, bf16x8 pa2, bf16x8 pa3) {
; #pragma unroll
;     for (int d0 = 0; d0 < 2; ++d0) { s16x4 lo[4], hi[4];
; #pragma unroll
;         for (int ks = 0; ks < 4; ++ks) {
;             asm volatile("ds_read_b64_tr_b16 %0,%1 offset:%c2" : "=&v"(lo[ks]) : "v"(vb), "i"(d0 * 4096 + ks * 1024) : "memory");
;             asm volatile("ds_read_b64_tr_b16 %0,%1 offset:%c2" : "=&v"(hi[ks]) : "v"(vb), "i"(d0 * 4096 + ks * 1024 + 512) : "memory"); }
;         asm volatile("s_waitcnt lgkmcnt(0)" ::: "memory"); AT_SBAR();
;     ...
;         o[d0] = __builtin_amdgcn_mfma_f32_32x32x16_bf16(pa0, AT_PK(0), o[d0], 0, 0, 0);
;         o[d0] = __builtin_amdgcn_mfma_f32_32x32x16_bf16(pa1, AT_PK(1), o[d0], 0, 0, 0);
;         o[d0] = __builtin_amdgcn_mfma_f32_32x32x16_bf16(pa2, AT_PK(2), o[d0], 0, 0, 0);
;         o[d0] = __builtin_amdgcn_mfma_f32_32x32x16_bf16(pa3, AT_PK(3), o[d0], 0, 0, 0);
;     ...
;     }
; }
; __device__ __forceinline__ void store_tile(const f32x16* o, const float* rli, bf16_t* stg, bf16_t* Ow, int pitch, float* ss, int lane, int r32, int hi) {
; #pragma unroll
;     for (int r = 0; r < 16; ++r) { const int orow = crow(r, hi);
; #pragma unroll
;         for (int d0 = 0; d0 < 2; ++d0) stg[orow * 64 + d0 * 32 + r32] = (bf16_t)(cvtpk_s(o[d0][r] * rli[r], 0.f) & 0xffffu); }
;     ...
;     { float sacc = pB0[0] + pB0[1]; _Pragma("unroll") for (int r = 2; r < 16; ++r) sacc += pB0[r]; _Pragma("unroll") for (int r = 0; r < 16; ++r) sacc += pB1[r]; l_reg += sacc;
;       pw0 = (u32x4){PKW(pB0, 0), PKW(pB0, 2), PKW(pB0, 4), PKW(pB0, 6)}; pw1 = (u32x4){PKW(pB0, 8), PKW(pB0, 10), PKW(pB0, 12), PKW(pB0, 14)}; pw2 = (u32x4){PKW(pB1, 0), PKW(pB1, 2), PKW(pB1, 4), PKW(pB1, 6)}; pw3 = (u32x4){PKW(pB1, 8), PKW(pB1, 10), PKW(pB1, 12), PKW(pB1, 14)};
;       SBAR(); const int vb0 = (int)(lds0 + LDS_V) + ((lane >> 4) & 1) * 32 + (lane & 3) * 8 + (4 * hi + ((lane & 15) >> 2)) * 64;
;       at::pv(o, vb0 + sl_cur, PAF(0), PAF(1), PAF(2), PAF(3)); }
;     ...
;     { auto rr = __builtin_amdgcn_permlane32_swap(__float_as_uint(l_reg), __float_as_uint(l_reg), false, false); l_reg = __uint_as_float(rr[0]) + __uint_as_float(rr[1]); }
;     if (hi == 0) wsf[32 + r32] = l_reg; asm volatile("s_waitcnt lgkmcnt(0)" ::: "memory");
;     float rli[16];
; #pragma unroll
;     for (int r = 0; r < 16; ++r) rli[r] = __builtin_amdgcn_rcpf(wsf[32 + crow(r, hi)]);
	v_mfma_f32_32x32x16_bf16 v[18:33], v[2:5], v[110:113], v[18:33]
	v_cvt_pk_bf16_f32 v7, v52, v53
	v_cvt_pk_bf16_f32 v8, v54, v55
	v_cvt_pk_bf16_f32 v9, v56, v57
	v_cvt_pk_bf16_f32 v50, v58, v59
	v_cvt_pk_bf16_f32 v51, v60, v61
	v_cvt_pk_bf16_f32 v52, v62, v63
	v_cvt_pk_bf16_f32 v53, v64, v65
	s_waitcnt lgkmcnt(0)
	v_mfma_f32_32x32x16_bf16 v[34:49], v[2:5], v[70:73], v[34:49]
	v_add_u32_e32 v2, s16, v188
	v_add3_u32 v66, v2, v187, v189
	ds_read_b64_tr_b16 v[2:3],v66 offset:0
	ds_read_b64_tr_b16 v[4:5],v66 offset:512
	ds_read_b64_tr_b16 v[54:55],v66 offset:1024
	ds_read_b64_tr_b16 v[56:57],v66 offset:1536
	ds_read_b64_tr_b16 v[58:59],v66 offset:2048
	ds_read_b64_tr_b16 v[60:61],v66 offset:2560
	ds_read_b64_tr_b16 v[62:63],v66 offset:3072
	ds_read_b64_tr_b16 v[64:65],v66 offset:3584
	s_waitcnt lgkmcnt(0)
	s_nop 0
	v_mfma_f32_32x32x16_bf16 v[18:33], v[76:79], v[2:5], v[18:33]
	ds_read_b64_tr_b16 v[2:3],v66 offset:4096
	ds_read_b64_tr_b16 v[4:5],v66 offset:4608
	v_mfma_f32_32x32x16_bf16 v[18:33], v[10:13], v[54:57], v[18:33]
	ds_read_b64_tr_b16 v[54:55],v66 offset:5120
	ds_read_b64_tr_b16 v[56:57],v66 offset:5632
	v_mfma_f32_32x32x16_bf16 v[18:33], v[6:9], v[58:61], v[18:33]
	ds_read_b64_tr_b16 v[58:59],v66 offset:6144
	ds_read_b64_tr_b16 v[60:61],v66 offset:6656
	v_mfma_f32_32x32x16_bf16 v[18:33], v[50:53], v[62:65], v[18:33]
	ds_read_b64_tr_b16 v[62:63],v66 offset:7168
	ds_read_b64_tr_b16 v[64:65],v66 offset:7680
	s_waitcnt lgkmcnt(0)
	v_mfma_f32_32x32x16_bf16 v[34:49], v[76:79], v[2:5], v[34:49]
	v_mov_b32_e32 v2, v74
	s_nop 1
	v_permlane32_swap_b32_e32 v74, v2
	v_cmp_gt_u32_e32 vcc, 32, v15
	v_mfma_f32_32x32x16_bf16 v[34:49], v[10:13], v[54:57], v[34:49]
	v_mfma_f32_32x32x16_bf16 v[34:49], v[6:9], v[58:61], v[34:49]
	v_mfma_f32_32x32x16_bf16 v[34:49], v[50:53], v[62:65], v[34:49]
	s_and_saveexec_b64 s[12:13], vcc
	v_add_f32_e32 v2, v74, v2
	v_lshl_add_u32 v3, v17, 2, s2
	ds_write_b32 v3, v2 offset:49280
	s_or_b64 exec, exec, s[12:13]
	s_waitcnt lgkmcnt(0)
	v_lshl_add_u32 v10, v186, 4, s2
	ds_read_b128 v[2:5], v10 offset:49280
	ds_read_b128 v[6:9], v10 offset:49312
	s_lshl_b64 s[12:13], s[4:5], 11
	s_add_u32 s10, s10, s12
	s_addc_u32 s11, s11, s13
	s_lshl_b64 s[4:5], s[4:5], 4
	s_add_u32 s8, s8, s4
	s_waitcnt lgkmcnt(1)
	v_rcp_f32_e32 v11, v2
	s_addc_u32 s2, s9, s5
	s_add_u32 s6, s10, s6
	s_addc_u32 s7, s11, s7
	s_lshl_b32 s4, s19, 12
	v_rcp_f32_e32 v12, v3
	v_rcp_f32_e32 v13, v4
	v_rcp_f32_e32 v50, v5
	s_waitcnt lgkmcnt(0)
	v_rcp_f32_e32 v51, v6
	ds_read_b128 v[2:5], v10 offset:49344
	v_rcp_f32_e32 v52, v7
	v_rcp_f32_e32 v53, v8
	v_rcp_f32_e32 v54, v9
	ds_read_b128 v[6:9], v10 offset:49376
	s_add_i32 s9, s4, 0
	v_mul_f32_e32 v10, v18, v11
	v_lshlrev_b32_e32 v0, 1, v0
	v_lshlrev_b32_e32 v17, 1, v17
	v_cvt_pk_bf16_f32 v10, v10, s0
	v_add3_u32 v0, s9, v0, v17
	ds_write_b16 v0, v10 offset:51200
	v_mul_f32_e32 v10, v34, v11
	v_cvt_pk_bf16_f32 v10, v10, s0
	ds_write_b16 v0, v10 offset:51264
	v_mul_f32_e32 v10, v19, v12
	v_cvt_pk_bf16_f32 v10, v10, s0
	ds_write_b16 v0, v10 offset:51328
	v_mul_f32_e32 v10, v35, v12
	v_cvt_pk_bf16_f32 v10, v10, s0
	ds_write_b16 v0, v10 offset:51392
	v_mul_f32_e32 v10, v20, v13
	v_cvt_pk_bf16_f32 v10, v10, s0
	ds_write_b16 v0, v10 offset:51456
	v_mul_f32_e32 v10, v36, v13
	v_cvt_pk_bf16_f32 v10, v10, s0
	ds_write_b16 v0, v10 offset:51520
	v_mul_f32_e32 v10, v21, v50
	v_cvt_pk_bf16_f32 v10, v10, s0
	ds_write_b16 v0, v10 offset:51584
	v_mul_f32_e32 v10, v37, v50
	v_cvt_pk_bf16_f32 v10, v10, s0
	ds_write_b16 v0, v10 offset:51648
	v_mul_f32_e32 v10, v22, v51
	v_cvt_pk_bf16_f32 v10, v10, s0
	ds_write_b16 v0, v10 offset:52224
	v_mul_f32_e32 v10, v38, v51
	v_cvt_pk_bf16_f32 v10, v10, s0
	ds_write_b16 v0, v10 offset:52288
	v_mul_f32_e32 v10, v23, v52
	v_cvt_pk_bf16_f32 v10, v10, s0
	ds_write_b16 v0, v10 offset:52352
	v_mul_f32_e32 v10, v39, v52
	v_cvt_pk_bf16_f32 v10, v10, s0
	ds_write_b16 v0, v10 offset:52416
	v_mul_f32_e32 v10, v24, v53
	v_cvt_pk_bf16_f32 v10, v10, s0
	ds_write_b16 v0, v10 offset:52480
	v_mul_f32_e32 v10, v40, v53
	v_cvt_pk_bf16_f32 v10, v10, s0
	s_waitcnt lgkmcnt(14)
; __device__ __forceinline__ int crow(int r, int hi) { return (r & 3) + 8 * (r >> 2) + 4 * hi; }
; __device__ __forceinline__ unsigned cvtpk_s(float lo, float hi) { typedef __bf16 bf16x2_t __attribute__((ext_vector_type(2))); f32x2 v = {lo, hi}; bf16x2_t b = __builtin_convertvector(v, bf16x2_t); return __builtin_bit_cast(unsigned, b); }
; __device__ __forceinline__ void store_tile(const f32x16* o, const float* rli, bf16_t* stg, bf16_t* Ow, int pitch, float* ss, int lane, int r32, int hi) {
; #pragma unroll
;     for (int r = 0; r < 16; ++r) { const int orow = crow(r, hi);
; #pragma unroll
;         for (int d0 = 0; d0 < 2; ++d0) stg[orow * 64 + d0 * 32 + r32] = (bf16_t)(cvtpk_s(o[d0][r] * rli[r], 0.f) & 0xffffu); }
;     asm volatile("s_waitcnt lgkmcnt(0)" ::: "memory");
; #pragma unroll
;     for (int i = 0; i < 4; ++i) { const int row = i * 8 + (lane >> 3), ch = lane & 7; const u32x4 v = *(const u32x4*)(stg + row * 64 + ch * 8);
;         { const bf16_t* gp_ = Ow + (long)row * pitch + ch * 8; asm volatile("global_store_dwordx4 %0, %1, off sc0 sc1\n\ts_nop 1" :: "v"(gp_), "v"(v) : "memory"); }
;         float s = 0.f;
; #pragma unroll
;         for (int j = 0; j < 4; ++j) { const float a = __uint_as_float(v[j] << 16), b = __uint_as_float(v[j] & 0xffff0000u); s += a * a + b * b; }
;         s += __shfl_xor(s, 1); s += __shfl_xor(s, 2); s += __shfl_xor(s, 4);
;         if (ch == 0) atomicAdd(ss + (long)row * 4, s); }
;     asm volatile("s_waitcnt lgkmcnt(0)" ::: "memory");
; }
	v_rcp_f32_e32 v2, v2
	ds_write_b16 v0, v10 offset:52544
	v_mul_f32_e32 v10, v25, v54
	v_cvt_pk_bf16_f32 v10, v10, s0
	v_rcp_f32_e32 v3, v3
	ds_write_b16 v0, v10 offset:52608
	v_mul_f32_e32 v10, v41, v54
	v_cvt_pk_bf16_f32 v10, v10, s0
	ds_write_b16 v0, v10 offset:52672
	v_mul_f32_e32 v10, v26, v2
	v_mul_f32_e32 v2, v42, v2
	v_cvt_pk_bf16_f32 v2, v2, s0
	v_rcp_f32_e32 v4, v4
	ds_write_b16 v0, v2 offset:53312
	v_mul_f32_e32 v2, v27, v3
	v_cvt_pk_bf16_f32 v2, v2, s0
	ds_write_b16 v0, v2 offset:53376
	v_mul_f32_e32 v2, v43, v3
	v_cvt_pk_bf16_f32 v2, v2, s0
	v_rcp_f32_e32 v5, v5
	ds_write_b16 v0, v2 offset:53440
	v_mul_f32_e32 v2, v28, v4
	v_cvt_pk_bf16_f32 v2, v2, s0
	ds_write_b16 v0, v2 offset:53504
	v_mul_f32_e32 v2, v44, v4
	v_cvt_pk_bf16_f32 v2, v2, s0
	s_waitcnt lgkmcnt(14)
	v_rcp_f32_e32 v6, v6
	ds_write_b16 v0, v2 offset:53568
	v_mul_f32_e32 v2, v29, v5
	v_cvt_pk_bf16_f32 v2, v2, s0
	ds_write_b16 v0, v2 offset:53632
	v_mul_f32_e32 v2, v45, v5
	v_cvt_pk_bf16_f32 v2, v2, s0
	v_rcp_f32_e32 v7, v7
	ds_write_b16 v0, v2 offset:53696
	v_mul_f32_e32 v2, v30, v6
	v_cvt_pk_bf16_f32 v2, v2, s0
	ds_write_b16 v0, v2 offset:54272
	v_mul_f32_e32 v2, v46, v6
	v_cvt_pk_bf16_f32 v2, v2, s0
	v_rcp_f32_e32 v8, v8
	ds_write_b16 v0, v2 offset:54336
	v_mul_f32_e32 v2, v31, v7
	v_cvt_pk_bf16_f32 v2, v2, s0
	ds_write_b16 v0, v2 offset:54400
	v_mul_f32_e32 v2, v47, v7
	v_cvt_pk_bf16_f32 v2, v2, s0
	v_rcp_f32_e32 v9, v9
	ds_write_b16 v0, v2 offset:54464
	v_mul_f32_e32 v2, v32, v8
	v_cvt_pk_bf16_f32 v2, v2, s0
	ds_write_b16 v0, v2 offset:54528
	v_mul_f32_e32 v2, v48, v8
	v_cvt_pk_bf16_f32 v2, v2, s0
	ds_write_b16 v0, v2 offset:54592
	v_mul_f32_e32 v2, v33, v9
	v_cvt_pk_bf16_f32 v2, v2, s0
	ds_write_b16 v0, v2 offset:54656
	v_mul_f32_e32 v2, v49, v9
	v_cvt_pk_bf16_f32 v10, v10, s0
	v_cvt_pk_bf16_f32 v2, v2, s0
	v_and_b32_e32 v6, 7, v14
	ds_write_b16 v0, v10 offset:53248
	ds_write_b16 v0, v2 offset:54720
	v_lshlrev_b32_e32 v0, 4, v6
	v_lshrrev_b32_e32 v7, 3, v15
	v_add_u32_e32 v8, s9, v0
	s_waitcnt lgkmcnt(0)
	v_lshl_add_u32 v2, v7, 7, v8
	ds_read_b128 v[12:15], v2 offset:51200
	s_lshl_b64 s[4:5], s[0:1], 11
	s_add_u32 s6, s6, s4
	s_addc_u32 s7, s7, s5
	s_lshl_b64 s[0:1], s[0:1], 4
	s_waitcnt lgkmcnt(0)
	v_and_b32_e32 v3, 0xffff0000, v12
	v_lshlrev_b32_e32 v2, 16, v12
	v_mul_f32_e32 v3, v3, v3
	v_and_b32_e32 v4, 0xffff0000, v13
	v_fmac_f32_e32 v3, v2, v2
	v_lshlrev_b32_e32 v2, 16, v13
	v_mul_f32_e32 v4, v4, v4
	v_fmac_f32_e32 v4, v2, v2
	v_add_f32_e32 v2, v3, v4
	v_and_b32_e32 v4, 0xffff0000, v14
	v_lshlrev_b32_e32 v3, 16, v14
	v_mul_f32_e32 v4, v4, v4
	v_fmac_f32_e32 v4, v3, v3
	v_add_f32_e32 v2, v4, v2
	v_and_b32_e32 v4, 0xffff0000, v15
	v_lshlrev_b32_e32 v3, 16, v15
	v_mul_f32_e32 v4, v4, v4
	v_fmac_f32_e32 v4, v3, v3
	v_and_b32_e32 v3, 64, v220
	v_add_f32_e32 v5, v4, v2
	v_xor_b32_e32 v2, 1, v220
	v_add_u32_e32 v10, 64, v3
	v_cmp_lt_i32_e32 vcc, v2, v10
	s_add_u32 s0, s8, s0
	s_addc_u32 s1, s2, s1
	v_cndmask_b32_e32 v2, v220, v2, vcc
	v_lshlrev_b32_e32 v4, 2, v2
	ds_bpermute_b32 v9, v4, v5
	v_lshl_add_u64 v[2:3], s[6:7], 0, v[0:1]
	v_xor_b32_e32 v0, 2, v220
	v_cmp_lt_i32_e32 vcc, v0, v10
	s_add_u32 s4, s0, 0x200008
	s_waitcnt lgkmcnt(0)
	v_add_f32_e32 v9, v5, v9
	v_cndmask_b32_e32 v0, v220, v0, vcc
	v_lshlrev_b32_e32 v5, 2, v0
	s_addc_u32 s5, s1, 0
	ds_bpermute_b32 v11, v5, v9
	s_mov_b64 s[0:1], 0x12e40500
	v_lshl_add_u64 v[2:3], v[2:3], 0, s[0:1]
	v_lshlrev_b32_e32 v0, 11, v7
	v_lshl_add_u64 v[18:19], v[2:3], 0, v[0:1]
	v_xor_b32_e32 v0, 4, v220
	v_cmp_lt_i32_e64 s[0:1], v0, v10
	v_cmp_eq_u32_e32 vcc, 0, v6
	s_waitcnt lgkmcnt(0)
	v_add_f32_e32 v9, v9, v11
	v_cndmask_b32_e64 v0, v220, v0, s[0:1]
	v_lshlrev_b32_e32 v6, 2, v0
	ds_bpermute_b32 v10, v6, v9
	global_store_dwordx4 v[18:19], v[12:15], off sc0 sc1
	s_nop 1
	s_and_saveexec_b64 s[0:1], vcc
	v_readlane_b32 s36, v253, 25
	v_readlane_b32 s37, v253, 26
	v_readlane_b32 s38, v253, 27
	v_readlane_b32 s39, v253, 28
	v_readlane_b32 s40, v253, 29
	v_readlane_b32 s41, v253, 30
	v_readlane_b32 s42, v253, 31
	v_readlane_b32 s43, v253, 32
	v_readlane_b32 s44, v253, 33
	v_readlane_b32 s45, v253, 34
	v_readlane_b32 s46, v253, 35
	v_readlane_b32 s47, v253, 36
	v_readlane_b32 s48, v253, 37
	v_readlane_b32 s49, v253, 38
	v_readlane_b32 s50, v253, 39
	v_readlane_b32 s51, v253, 40
	s_cbranch_execz .LBB0_881
	v_lshlrev_b32_e32 v0, 4, v7
	v_lshl_add_u64 v[12:13], s[4:5], 0, v[0:1]
	s_waitcnt lgkmcnt(0)
	v_add_f32_e32 v0, v9, v10
	flat_atomic_add_f32 v[12:13], v0
